# RWKV prompt job: bonus output (rk*v) stored by the staging waves instead of the scan waves
# speedup vs baseline: 1.0005x; 1.0005x over previous
.Lrw_stage2_prev:
	global_load_dwordx2 v[228:229], v33, s[24:25]
	global_load_dwordx2 v[230:231], v33, s[24:25] offset:1024
	global_load_dwordx2 v[232:233], v33, s[24:25] offset:2048
	s_mov_b64 exec, s[70:71]
	global_load_dwordx2 v[234:235], v34, s[24:25]
	global_load_dwordx2 v[236:237], v35, s[24:25]
	global_load_dword v238, v36, s[24:25]
	v_add_u32_e32 v36, 0x84000, v36
	global_load_dword v239, v36, s[24:25]
	s_lshl_b32 s58, s95, 5
	s_add_u32 s58, s58, 16
	v_add_u32_e32 v37, s58, v219
	v_mul_u32_u24_e32 v32, 0x2600, v37
	v_add_u32_e32 v32, v32, v240
	v_add_u32_e32 v33, 0xffffda00, v32
	v_lshl_add_u32 v34, v37, 10, v241
	v_lshl_add_u32 v35, v37, 10, v242
	v_lshl_add_u32 v36, v37, 5, v246
	global_load_dwordx2 v[182:183], v32, s[24:25]
	global_load_dwordx2 v[184:185], v32, s[24:25] offset:1024
	global_load_dwordx2 v[186:187], v32, s[24:25] offset:2048
	v_mov_b32_e32 v188, 0
	v_mov_b32_e32 v189, 0
	v_mov_b32_e32 v190, 0
	v_mov_b32_e32 v191, 0
	v_mov_b32_e32 v192, 0
	v_mov_b32_e32 v193, 0
	global_load_dwordx2 v[188:189], v33, s[24:25]
	global_load_dwordx2 v[190:191], v33, s[24:25] offset:1024
	global_load_dwordx2 v[192:193], v33, s[24:25] offset:2048
	global_load_dwordx2 v[194:195], v34, s[24:25]
	global_load_dwordx2 v[196:197], v35, s[24:25]
	global_load_dword v198, v36, s[24:25]
	v_add_u32_e32 v36, 0x84000, v36
	global_load_dword v199, v36, s[24:25]
	s_and_b32 s58, s95, 1
	s_mul_i32 s59, s58, 0xc000
	s_lshl_b32 s58, s58, 7
	v_add_u32_e32 v245, s59, v243
	v_add_u32_e32 v247, s58, v244
	s_waitcnt vmcnt(10)
	v_lshlrev_b32_e32 v32, 16, v222
	v_and_b32_e32 v33, 0xffff0000, v222
	v_lshlrev_b32_e32 v34, 16, v223
	v_and_b32_e32 v35, 0xffff0000, v223
	v_lshlrev_b32_e32 v36, 16, v228
	v_and_b32_e32 v37, 0xffff0000, v228
	v_lshlrev_b32_e32 v38, 16, v229
	v_and_b32_e32 v39, 0xffff0000, v229
	v_sub_f32_e32 v36, v36, v32
	v_sub_f32_e32 v37, v37, v33
	v_sub_f32_e32 v38, v38, v34
	v_sub_f32_e32 v39, v39, v35
	v_pk_fma_f32 v[36:37], v[4:5], v[36:37], v[32:33]
	v_pk_fma_f32 v[38:39], v[6:7], v[38:39], v[34:35]
	ds_write_b128 v245, v[36:39] offset:1024
	v_lshlrev_b32_e32 v32, 16, v226
	v_and_b32_e32 v33, 0xffff0000, v226
	v_lshlrev_b32_e32 v34, 16, v227
	v_and_b32_e32 v35, 0xffff0000, v227
	v_lshlrev_b32_e32 v40, 16, v232
	v_and_b32_e32 v41, 0xffff0000, v232
	v_lshlrev_b32_e32 v42, 16, v233
	v_and_b32_e32 v43, 0xffff0000, v233
	v_sub_f32_e32 v40, v40, v32
	v_sub_f32_e32 v41, v41, v33
	v_sub_f32_e32 v42, v42, v34
	v_sub_f32_e32 v43, v43, v35
	v_pk_fma_f32 v[40:41], v[12:13], v[40:41], v[32:33]
	v_pk_fma_f32 v[42:43], v[14:15], v[42:43], v[34:35]
	ds_write_b128 v245, v[40:43] offset:1280
	v_lshrrev_b32_e32 v36, 3, v210
	v_cmp_eq_u32_e32 vcc, s28, v36
	s_and_saveexec_b64 s[70:71], vcc
	s_lshl_b32 s58, s95, 5
	v_add_u32_e32 v36, s58, v219
	v_lshlrev_b32_e32 v36, 10, v36
	v_lshl_add_u32 v36, v210, 3, v36
	v_mul_f32_e32 v32, v239, v40
	v_mul_f32_e32 v33, v239, v41
	v_mul_f32_e32 v34, v239, v42
	v_mul_f32_e32 v35, v239, v43
	v_bfe_u32 v37, v32, 16, 1
	v_add3_u32 v32, v32, v37, s78
	v_bfe_u32 v37, v33, 16, 1
	v_add3_u32 v33, v33, v37, s78
	v_bfe_u32 v37, v34, 16, 1
	v_add3_u32 v34, v34, v37, s78
	v_bfe_u32 v37, v35, 16, 1
	v_add3_u32 v35, v35, v37, s78
	s_mov_b32 s58, 0x7060302
	v_perm_b32 v32, v33, v32, s58
	v_perm_b32 v33, v35, v34, s58
	global_store_dwordx2 v36, v[32:33], s[44:45]
	s_or_b64 exec, exec, s[70:71]
	v_lshlrev_b32_e32 v32, 16, v224
	v_and_b32_e32 v33, 0xffff0000, v224
	v_lshlrev_b32_e32 v34, 16, v225
	v_and_b32_e32 v35, 0xffff0000, v225
	v_lshlrev_b32_e32 v44, 16, v230
	v_and_b32_e32 v45, 0xffff0000, v230
	v_lshlrev_b32_e32 v46, 16, v231
	v_and_b32_e32 v47, 0xffff0000, v231
	v_sub_f32_e32 v44, v44, v32
	v_sub_f32_e32 v45, v45, v33
	v_sub_f32_e32 v46, v46, v34
	v_sub_f32_e32 v47, v47, v35
	v_pk_fma_f32 v[44:45], v[8:9], v[44:45], v[32:33]
	v_pk_fma_f32 v[46:47], v[10:11], v[46:47], v[34:35]
	v_lshlrev_b32_e32 v60, 16, v234
	v_and_b32_e32 v61, 0xffff0000, v234
	v_lshlrev_b32_e32 v62, 16, v235
	v_and_b32_e32 v63, 0xffff0000, v235
	v_mul_f32_e32 v60, 0x3fb8aa3b, v60
	v_mul_f32_e32 v61, 0x3fb8aa3b, v61
	v_mul_f32_e32 v62, 0x3fb8aa3b, v62
	v_mul_f32_e32 v63, 0x3fb8aa3b, v63
	v_exp_f32_e32 v60, v60
	v_exp_f32_e32 v61, v61
	v_exp_f32_e32 v62, v62
	v_exp_f32_e32 v63, v63
	v_pk_mul_f32 v[48:49], v[16:17], v[44:45]
	v_pk_mul_f32 v[50:51], v[18:19], v[46:47]
	v_pk_mul_f32 v[48:49], v[48:49], v[238:239] op_sel_hi:[1,0]
	v_pk_mul_f32 v[50:51], v[50:51], v[238:239] op_sel_hi:[1,0]
	ds_write_b128 v245, v[48:51] offset:256
	v_lshlrev_b32_e32 v52, 16, v236
	v_and_b32_e32 v53, 0xffff0000, v236
	v_lshlrev_b32_e32 v54, 16, v237
	v_and_b32_e32 v55, 0xffff0000, v237
	v_pk_mul_f32 v[56:57], v[48:49], v[52:53]
	v_pk_mul_f32 v[58:59], v[50:51], v[54:55]
	ds_write_b128 v245, v[56:59] offset:512
	v_pk_add_f32 v[52:53], v[52:53], -1.0 op_sel_hi:[1,0]
	v_pk_add_f32 v[54:55], v[54:55], -1.0 op_sel_hi:[1,0]
	v_pk_fma_f32 v[52:53], v[20:21], v[52:53], 1.0 op_sel_hi:[1,1,0]
	v_pk_fma_f32 v[54:55], v[22:23], v[54:55], 1.0 op_sel_hi:[1,1,0]
	v_pk_mul_f32 v[52:53], v[44:45], v[52:53]
	v_pk_mul_f32 v[54:55], v[46:47], v[54:55]
	ds_write_b128 v245, v[52:55] offset:768
	ds_write_b128 v245, v[60:63]
	ds_write_b32 v247, v239
	s_waitcnt vmcnt(1)
	v_lshlrev_b32_e32 v32, 16, v182
	v_and_b32_e32 v33, 0xffff0000, v182
	v_lshlrev_b32_e32 v34, 16, v183
	v_and_b32_e32 v35, 0xffff0000, v183
	v_lshlrev_b32_e32 v36, 16, v188
	v_and_b32_e32 v37, 0xffff0000, v188
	v_lshlrev_b32_e32 v38, 16, v189
	v_and_b32_e32 v39, 0xffff0000, v189
	v_sub_f32_e32 v36, v36, v32
	v_sub_f32_e32 v37, v37, v33
	v_sub_f32_e32 v38, v38, v34
	v_sub_f32_e32 v39, v39, v35
	v_pk_fma_f32 v[36:37], v[4:5], v[36:37], v[32:33]
	v_pk_fma_f32 v[38:39], v[6:7], v[38:39], v[34:35]
	ds_write_b128 v245, v[36:39] offset:25600
	v_lshlrev_b32_e32 v32, 16, v186
	v_and_b32_e32 v33, 0xffff0000, v186
	v_lshlrev_b32_e32 v34, 16, v187
	v_and_b32_e32 v35, 0xffff0000, v187
	v_lshlrev_b32_e32 v40, 16, v192
	v_and_b32_e32 v41, 0xffff0000, v192
	v_lshlrev_b32_e32 v42, 16, v193
	v_and_b32_e32 v43, 0xffff0000, v193
	v_sub_f32_e32 v40, v40, v32
	v_sub_f32_e32 v41, v41, v33
	v_sub_f32_e32 v42, v42, v34
	v_sub_f32_e32 v43, v43, v35
	v_pk_fma_f32 v[40:41], v[12:13], v[40:41], v[32:33]
	v_pk_fma_f32 v[42:43], v[14:15], v[42:43], v[34:35]
	ds_write_b128 v245, v[40:43] offset:25856
	v_lshrrev_b32_e32 v36, 3, v210
	v_cmp_eq_u32_e32 vcc, s28, v36
	s_and_saveexec_b64 s[70:71], vcc
	s_lshl_b32 s58, s95, 5
	s_add_u32 s58, s58, 16
	v_add_u32_e32 v36, s58, v219
	v_lshlrev_b32_e32 v36, 10, v36
	v_lshl_add_u32 v36, v210, 3, v36
	v_mul_f32_e32 v32, v199, v40
	v_mul_f32_e32 v33, v199, v41
	v_mul_f32_e32 v34, v199, v42
	v_mul_f32_e32 v35, v199, v43
	v_bfe_u32 v37, v32, 16, 1
	v_add3_u32 v32, v32, v37, s78
	v_bfe_u32 v37, v33, 16, 1
	v_add3_u32 v33, v33, v37, s78
	v_bfe_u32 v37, v34, 16, 1
	v_add3_u32 v34, v34, v37, s78
	v_bfe_u32 v37, v35, 16, 1
	v_add3_u32 v35, v35, v37, s78
	s_mov_b32 s58, 0x7060302
	v_perm_b32 v32, v33, v32, s58
	v_perm_b32 v33, v35, v34, s58
	global_store_dwordx2 v36, v[32:33], s[44:45]
	s_or_b64 exec, exec, s[70:71]
	v_lshlrev_b32_e32 v32, 16, v184
	v_and_b32_e32 v33, 0xffff0000, v184
	v_lshlrev_b32_e32 v34, 16, v185
	v_and_b32_e32 v35, 0xffff0000, v185
	v_lshlrev_b32_e32 v44, 16, v190
	v_and_b32_e32 v45, 0xffff0000, v190
	v_lshlrev_b32_e32 v46, 16, v191
	v_and_b32_e32 v47, 0xffff0000, v191
	v_sub_f32_e32 v44, v44, v32
	v_sub_f32_e32 v45, v45, v33
	v_sub_f32_e32 v46, v46, v34
	v_sub_f32_e32 v47, v47, v35
	v_pk_fma_f32 v[44:45], v[8:9], v[44:45], v[32:33]
	v_pk_fma_f32 v[46:47], v[10:11], v[46:47], v[34:35]
	v_lshlrev_b32_e32 v60, 16, v194
	v_and_b32_e32 v61, 0xffff0000, v194
	v_lshlrev_b32_e32 v62, 16, v195
	v_and_b32_e32 v63, 0xffff0000, v195
	v_mul_f32_e32 v60, 0x3fb8aa3b, v60
	v_mul_f32_e32 v61, 0x3fb8aa3b, v61
	v_mul_f32_e32 v62, 0x3fb8aa3b, v62
	v_mul_f32_e32 v63, 0x3fb8aa3b, v63
	v_exp_f32_e32 v60, v60
	v_exp_f32_e32 v61, v61
	v_exp_f32_e32 v62, v62
	v_exp_f32_e32 v63, v63
	v_pk_mul_f32 v[48:49], v[16:17], v[44:45]
	v_pk_mul_f32 v[50:51], v[18:19], v[46:47]
	v_pk_mul_f32 v[48:49], v[48:49], v[198:199] op_sel_hi:[1,0]
	v_pk_mul_f32 v[50:51], v[50:51], v[198:199] op_sel_hi:[1,0]
	ds_write_b128 v245, v[48:51] offset:24832
	v_lshlrev_b32_e32 v52, 16, v196
	v_and_b32_e32 v53, 0xffff0000, v196
	v_lshlrev_b32_e32 v54, 16, v197
	v_and_b32_e32 v55, 0xffff0000, v197
	v_pk_mul_f32 v[56:57], v[48:49], v[52:53]
	v_pk_mul_f32 v[58:59], v[50:51], v[54:55]
	ds_write_b128 v245, v[56:59] offset:25088
	v_pk_add_f32 v[52:53], v[52:53], -1.0 op_sel_hi:[1,0]
	v_pk_add_f32 v[54:55], v[54:55], -1.0 op_sel_hi:[1,0]
	v_pk_fma_f32 v[52:53], v[20:21], v[52:53], 1.0 op_sel_hi:[1,1,0]
	v_pk_fma_f32 v[54:55], v[22:23], v[54:55], 1.0 op_sel_hi:[1,1,0]
	v_pk_mul_f32 v[52:53], v[44:45], v[52:53]
	v_pk_mul_f32 v[54:55], v[46:47], v[54:55]
	ds_write_b128 v245, v[52:55] offset:25344
	ds_write_b128 v245, v[60:63] offset:24576
	ds_write_b32 v247, v199 offset:64
	s_branch .LBB0_653
.Lrw_fast:
	s_setprio 3
	s_and_b32 s89, s64, 1
	s_mul_i32 s89, s89, 0xc000
	v_lshl_add_u32 v112, s28, 5, v81
	v_lshl_add_u32 v124, v84, 2, s89
	v_lshl_add_u32 v135, v112, 2, s89
	ds_read_b128 v[76:79], v124 offset:272
	ds_read_b128 v[72:75], v124 offset:256
	ds_read_b128 v[68:71], v124 offset:512
	ds_read_b128 v[56:59], v124 offset:528
	ds_read_b32 v0, v135 offset:1280
	ds_read_b128 v[64:67], v124 offset:768
	ds_read_b128 v[60:63], v124 offset:784
	ds_read_b128 v[48:51], v124 offset:0
	ds_read_b128 v[40:43], v124 offset:16
	ds_read_b128 v[52:55], v124 offset:1040
	ds_read_b128 v[44:47], v124 offset:1024
	ds_read_b128 v[156:159], v124 offset:1808
	ds_read_b128 v[152:155], v124 offset:1792
	ds_read_b128 v[182:185], v124 offset:2048
	ds_read_b128 v[186:189], v124 offset:2064
	ds_read_b32 v160, v135 offset:2816
	ds_read_b128 v[190:193], v124 offset:2304
	ds_read_b128 v[194:197], v124 offset:2320
	ds_read_b128 v[144:147], v124 offset:1536
	ds_read_b128 v[148:151], v124 offset:1552
	ds_read_b128 v[202:205], v124 offset:2576
	ds_read_b128 v[198:201], v124 offset:2560
	s_waitcnt lgkmcnt(11)
	v_pk_mul_f32 v[76:77], v[32:33], v[76:77]
	v_pk_mul_f32 v[78:79], v[34:35], v[78:79]
	v_pk_fma_f32 v[72:73], v[36:37], v[72:73], v[76:77]
	v_pk_fma_f32 v[74:75], v[38:39], v[74:75], v[78:79]
	v_pk_add_f32 v[72:73], v[72:73], v[74:75]
	v_add_f32_e32 v142, v72, v73
	s_nop 1
	v_add_f32_dpp v142, v142, v142 quad_perm:[1,0,3,2] row_mask:0xf bank_mask:0xf bound_ctrl:1
	s_nop 1
	v_add_f32_dpp v142, v142, v142 quad_perm:[2,3,0,1] row_mask:0xf bank_mask:0xf bound_ctrl:1
	s_nop 1
	v_add_f32_dpp v142, v142, v142 row_half_mirror row_mask:0xf bank_mask:0xf bound_ctrl:1
	v_pk_mul_f32 v[68:69], v[68:69], v[142:143] op_sel_hi:[1,0]
	v_pk_mul_f32 v[70:71], v[70:71], v[142:143] op_sel_hi:[1,0]
	v_pk_mul_f32 v[56:57], v[56:57], v[142:143] op_sel_hi:[1,0]
	v_pk_mul_f32 v[58:59], v[58:59], v[142:143] op_sel_hi:[1,0]
	v_pk_fma_f32 v[64:65], v[64:65], v[0:1], v[68:69] op_sel_hi:[1,0,1] neg_lo:[0,0,1] neg_hi:[0,0,1]
	v_pk_fma_f32 v[66:67], v[66:67], v[0:1], v[70:71] op_sel_hi:[1,0,1] neg_lo:[0,0,1] neg_hi:[0,0,1]
	v_pk_fma_f32 v[60:61], v[60:61], v[0:1], v[56:57] op_sel_hi:[1,0,1] neg_lo:[0,0,1] neg_hi:[0,0,1]
	v_pk_fma_f32 v[62:63], v[62:63], v[0:1], v[58:59] op_sel_hi:[1,0,1] neg_lo:[0,0,1] neg_hi:[0,0,1]
	v_pk_fma_f32 v[36:37], v[36:37], v[48:49], v[64:65]
	v_pk_fma_f32 v[38:39], v[38:39], v[50:51], v[66:67]
	v_pk_fma_f32 v[32:33], v[32:33], v[40:41], v[60:61]
	v_pk_fma_f32 v[34:35], v[34:35], v[42:43], v[62:63]
	s_waitcnt lgkmcnt(2)
	v_pk_mul_f32 v[156:157], v[32:33], v[156:157]
	v_pk_mul_f32 v[52:53], v[32:33], v[52:53]
	v_pk_mul_f32 v[158:159], v[34:35], v[158:159]
	v_pk_mul_f32 v[54:55], v[34:35], v[54:55]
	v_pk_fma_f32 v[152:153], v[36:37], v[152:153], v[156:157]
	v_pk_fma_f32 v[44:45], v[36:37], v[44:45], v[52:53]
	v_pk_fma_f32 v[154:155], v[38:39], v[154:155], v[158:159]
	v_pk_fma_f32 v[46:47], v[38:39], v[46:47], v[54:55]
	v_pk_add_f32 v[152:153], v[152:153], v[154:155]
	v_pk_add_f32 v[44:45], v[44:45], v[46:47]
	v_add_f32_e32 v142, v152, v153
	v_add_f32_e32 v143, v44, v45
	ds_read_b128 v[76:79], v124 offset:3344
	v_add_f32_dpp v142, v142, v142 quad_perm:[1,0,3,2] row_mask:0xf bank_mask:0xf bound_ctrl:1
	v_add_f32_dpp v143, v143, v143 quad_perm:[1,0,3,2] row_mask:0xf bank_mask:0xf bound_ctrl:1
	ds_read_b128 v[72:75], v124 offset:3328
	v_add_f32_dpp v142, v142, v142 quad_perm:[2,3,0,1] row_mask:0xf bank_mask:0xf bound_ctrl:1
	v_add_f32_dpp v143, v143, v143 quad_perm:[2,3,0,1] row_mask:0xf bank_mask:0xf bound_ctrl:1
	ds_read_b128 v[68:71], v124 offset:3584
	v_add_f32_dpp v142, v142, v142 row_half_mirror row_mask:0xf bank_mask:0xf bound_ctrl:1
	v_add_f32_dpp v143, v143, v143 row_half_mirror row_mask:0xf bank_mask:0xf bound_ctrl:1
	ds_read_b128 v[56:59], v124 offset:3600
	ds_read_b32 v0, v135 offset:4352
	ds_read_b128 v[64:67], v124 offset:3840
	ds_read_b128 v[60:63], v124 offset:3856
	ds_read_b128 v[48:51], v124 offset:3072
	ds_read_b128 v[40:43], v124 offset:3088
	v_pk_mul_f32 v[182:183], v[182:183], v[142:143] op_sel_hi:[1,0]
	v_pk_mul_f32 v[184:185], v[184:185], v[142:143] op_sel_hi:[1,0]
	s_mov_b32 vcc_lo, 0x1010101
	v_pk_mul_f32 v[186:187], v[186:187], v[142:143] op_sel_hi:[1,0]
	v_pk_mul_f32 v[188:189], v[188:189], v[142:143] op_sel_hi:[1,0]
	s_mov_b32 vcc_hi, 0x1010101
	v_pk_fma_f32 v[190:191], v[190:191], v[160:161], v[182:183] op_sel_hi:[1,0,1] neg_lo:[0,0,1] neg_hi:[0,0,1]
	v_pk_fma_f32 v[192:193], v[192:193], v[160:161], v[184:185] op_sel_hi:[1,0,1] neg_lo:[0,0,1] neg_hi:[0,0,1]
	v_cndmask_b32_e32 v134, v134, v143, vcc
	v_pk_fma_f32 v[194:195], v[194:195], v[160:161], v[186:187] op_sel_hi:[1,0,1] neg_lo:[0,0,1] neg_hi:[0,0,1]
	v_pk_fma_f32 v[196:197], v[196:197], v[160:161], v[188:189] op_sel_hi:[1,0,1] neg_lo:[0,0,1] neg_hi:[0,0,1]
	ds_read_b128 v[52:55], v124 offset:4112
	ds_read_b128 v[44:47], v124 offset:4096
	v_pk_fma_f32 v[36:37], v[36:37], v[144:145], v[190:191]
	v_pk_fma_f32 v[38:39], v[38:39], v[146:147], v[192:193]
	v_pk_fma_f32 v[32:33], v[32:33], v[148:149], v[194:195]
	v_pk_fma_f32 v[34:35], v[34:35], v[150:151], v[196:197]
	s_waitcnt lgkmcnt(2)
	v_pk_mul_f32 v[76:77], v[32:33], v[76:77]
	v_pk_mul_f32 v[202:203], v[32:33], v[202:203]
	v_pk_mul_f32 v[78:79], v[34:35], v[78:79]
	v_pk_mul_f32 v[204:205], v[34:35], v[204:205]
	v_pk_fma_f32 v[72:73], v[36:37], v[72:73], v[76:77]
	v_pk_fma_f32 v[198:199], v[36:37], v[198:199], v[202:203]
	v_pk_fma_f32 v[74:75], v[38:39], v[74:75], v[78:79]
	v_pk_fma_f32 v[200:201], v[38:39], v[200:201], v[204:205]
	v_pk_add_f32 v[72:73], v[72:73], v[74:75]
	v_pk_add_f32 v[198:199], v[198:199], v[200:201]
	v_add_f32_e32 v142, v72, v73
	v_add_f32_e32 v143, v198, v199
	ds_read_b128 v[156:159], v124 offset:4880
	v_add_f32_dpp v142, v142, v142 quad_perm:[1,0,3,2] row_mask:0xf bank_mask:0xf bound_ctrl:1
	v_add_f32_dpp v143, v143, v143 quad_perm:[1,0,3,2] row_mask:0xf bank_mask:0xf bound_ctrl:1
	ds_read_b128 v[152:155], v124 offset:4864
	v_add_f32_dpp v142, v142, v142 quad_perm:[2,3,0,1] row_mask:0xf bank_mask:0xf bound_ctrl:1
	v_add_f32_dpp v143, v143, v143 quad_perm:[2,3,0,1] row_mask:0xf bank_mask:0xf bound_ctrl:1
	ds_read_b128 v[182:185], v124 offset:5120
	v_add_f32_dpp v142, v142, v142 row_half_mirror row_mask:0xf bank_mask:0xf bound_ctrl:1
	v_add_f32_dpp v143, v143, v143 row_half_mirror row_mask:0xf bank_mask:0xf bound_ctrl:1
	ds_read_b128 v[186:189], v124 offset:5136
	ds_read_b32 v160, v135 offset:5888
	ds_read_b128 v[190:193], v124 offset:5376
	ds_read_b128 v[194:197], v124 offset:5392
	ds_read_b128 v[144:147], v124 offset:4608
	ds_read_b128 v[148:151], v124 offset:4624
	v_pk_mul_f32 v[68:69], v[68:69], v[142:143] op_sel_hi:[1,0]
	v_pk_mul_f32 v[70:71], v[70:71], v[142:143] op_sel_hi:[1,0]
	s_mov_b32 vcc_lo, 0x2020202
	v_pk_mul_f32 v[56:57], v[56:57], v[142:143] op_sel_hi:[1,0]
	v_pk_mul_f32 v[58:59], v[58:59], v[142:143] op_sel_hi:[1,0]
	s_mov_b32 vcc_hi, 0x2020202
	v_pk_fma_f32 v[64:65], v[64:65], v[0:1], v[68:69] op_sel_hi:[1,0,1] neg_lo:[0,0,1] neg_hi:[0,0,1]
	v_pk_fma_f32 v[66:67], v[66:67], v[0:1], v[70:71] op_sel_hi:[1,0,1] neg_lo:[0,0,1] neg_hi:[0,0,1]
	v_cndmask_b32_e32 v134, v134, v143, vcc
	v_pk_fma_f32 v[60:61], v[60:61], v[0:1], v[56:57] op_sel_hi:[1,0,1] neg_lo:[0,0,1] neg_hi:[0,0,1]
	v_pk_fma_f32 v[62:63], v[62:63], v[0:1], v[58:59] op_sel_hi:[1,0,1] neg_lo:[0,0,1] neg_hi:[0,0,1]
	ds_read_b128 v[202:205], v124 offset:5648
	ds_read_b128 v[198:201], v124 offset:5632
	v_pk_fma_f32 v[36:37], v[36:37], v[48:49], v[64:65]
	v_pk_fma_f32 v[38:39], v[38:39], v[50:51], v[66:67]
	v_pk_fma_f32 v[32:33], v[32:33], v[40:41], v[60:61]
	v_pk_fma_f32 v[34:35], v[34:35], v[42:43], v[62:63]
	s_waitcnt lgkmcnt(2)
	v_pk_mul_f32 v[156:157], v[32:33], v[156:157]
	v_pk_mul_f32 v[52:53], v[32:33], v[52:53]
	v_pk_mul_f32 v[158:159], v[34:35], v[158:159]
	v_pk_mul_f32 v[54:55], v[34:35], v[54:55]
	v_pk_fma_f32 v[152:153], v[36:37], v[152:153], v[156:157]
	v_pk_fma_f32 v[44:45], v[36:37], v[44:45], v[52:53]
	v_pk_fma_f32 v[154:155], v[38:39], v[154:155], v[158:159]
	v_pk_fma_f32 v[46:47], v[38:39], v[46:47], v[54:55]
	v_pk_add_f32 v[152:153], v[152:153], v[154:155]
	v_pk_add_f32 v[44:45], v[44:45], v[46:47]
	v_add_f32_e32 v142, v152, v153
	v_add_f32_e32 v143, v44, v45
	ds_read_b128 v[76:79], v124 offset:6416
	v_add_f32_dpp v142, v142, v142 quad_perm:[1,0,3,2] row_mask:0xf bank_mask:0xf bound_ctrl:1
	v_add_f32_dpp v143, v143, v143 quad_perm:[1,0,3,2] row_mask:0xf bank_mask:0xf bound_ctrl:1
	ds_read_b128 v[72:75], v124 offset:6400
	v_add_f32_dpp v142, v142, v142 quad_perm:[2,3,0,1] row_mask:0xf bank_mask:0xf bound_ctrl:1
	v_add_f32_dpp v143, v143, v143 quad_perm:[2,3,0,1] row_mask:0xf bank_mask:0xf bound_ctrl:1
	ds_read_b128 v[68:71], v124 offset:6656
	v_add_f32_dpp v142, v142, v142 row_half_mirror row_mask:0xf bank_mask:0xf bound_ctrl:1
	v_add_f32_dpp v143, v143, v143 row_half_mirror row_mask:0xf bank_mask:0xf bound_ctrl:1
	ds_read_b128 v[56:59], v124 offset:6672
	ds_read_b32 v0, v135 offset:7424
	ds_read_b128 v[64:67], v124 offset:6912
	ds_read_b128 v[60:63], v124 offset:6928
	ds_read_b128 v[48:51], v124 offset:6144
	ds_read_b128 v[40:43], v124 offset:6160
	v_pk_mul_f32 v[182:183], v[182:183], v[142:143] op_sel_hi:[1,0]
	v_pk_mul_f32 v[184:185], v[184:185], v[142:143] op_sel_hi:[1,0]
	s_mov_b32 vcc_lo, 0x4040404
	v_pk_mul_f32 v[186:187], v[186:187], v[142:143] op_sel_hi:[1,0]
	v_pk_mul_f32 v[188:189], v[188:189], v[142:143] op_sel_hi:[1,0]
	s_mov_b32 vcc_hi, 0x4040404
	v_pk_fma_f32 v[190:191], v[190:191], v[160:161], v[182:183] op_sel_hi:[1,0,1] neg_lo:[0,0,1] neg_hi:[0,0,1]
	v_pk_fma_f32 v[192:193], v[192:193], v[160:161], v[184:185] op_sel_hi:[1,0,1] neg_lo:[0,0,1] neg_hi:[0,0,1]
	v_cndmask_b32_e32 v134, v134, v143, vcc
	v_pk_fma_f32 v[194:195], v[194:195], v[160:161], v[186:187] op_sel_hi:[1,0,1] neg_lo:[0,0,1] neg_hi:[0,0,1]
	v_pk_fma_f32 v[196:197], v[196:197], v[160:161], v[188:189] op_sel_hi:[1,0,1] neg_lo:[0,0,1] neg_hi:[0,0,1]
	ds_read_b128 v[52:55], v124 offset:7184
	ds_read_b128 v[44:47], v124 offset:7168
	v_pk_fma_f32 v[36:37], v[36:37], v[144:145], v[190:191]
	v_pk_fma_f32 v[38:39], v[38:39], v[146:147], v[192:193]
	v_pk_fma_f32 v[32:33], v[32:33], v[148:149], v[194:195]
	v_pk_fma_f32 v[34:35], v[34:35], v[150:151], v[196:197]
	s_waitcnt lgkmcnt(2)
	v_pk_mul_f32 v[76:77], v[32:33], v[76:77]
	v_pk_mul_f32 v[202:203], v[32:33], v[202:203]
	v_pk_mul_f32 v[78:79], v[34:35], v[78:79]
	v_pk_mul_f32 v[204:205], v[34:35], v[204:205]
	v_pk_fma_f32 v[72:73], v[36:37], v[72:73], v[76:77]
	v_pk_fma_f32 v[198:199], v[36:37], v[198:199], v[202:203]
	v_pk_fma_f32 v[74:75], v[38:39], v[74:75], v[78:79]
	v_pk_fma_f32 v[200:201], v[38:39], v[200:201], v[204:205]
	v_pk_add_f32 v[72:73], v[72:73], v[74:75]
	v_pk_add_f32 v[198:199], v[198:199], v[200:201]
	v_add_f32_e32 v142, v72, v73
	v_add_f32_e32 v143, v198, v199
	ds_read_b128 v[156:159], v124 offset:7952
	v_add_f32_dpp v142, v142, v142 quad_perm:[1,0,3,2] row_mask:0xf bank_mask:0xf bound_ctrl:1
	v_add_f32_dpp v143, v143, v143 quad_perm:[1,0,3,2] row_mask:0xf bank_mask:0xf bound_ctrl:1
	ds_read_b128 v[152:155], v124 offset:7936
	v_add_f32_dpp v142, v142, v142 quad_perm:[2,3,0,1] row_mask:0xf bank_mask:0xf bound_ctrl:1
	v_add_f32_dpp v143, v143, v143 quad_perm:[2,3,0,1] row_mask:0xf bank_mask:0xf bound_ctrl:1
	ds_read_b128 v[182:185], v124 offset:8192
	v_add_f32_dpp v142, v142, v142 row_half_mirror row_mask:0xf bank_mask:0xf bound_ctrl:1
	v_add_f32_dpp v143, v143, v143 row_half_mirror row_mask:0xf bank_mask:0xf bound_ctrl:1
	ds_read_b128 v[186:189], v124 offset:8208
	ds_read_b32 v160, v135 offset:8960
	ds_read_b128 v[190:193], v124 offset:8448
	ds_read_b128 v[194:197], v124 offset:8464
	ds_read_b128 v[144:147], v124 offset:7680
	ds_read_b128 v[148:151], v124 offset:7696
	v_pk_mul_f32 v[68:69], v[68:69], v[142:143] op_sel_hi:[1,0]
	v_pk_mul_f32 v[70:71], v[70:71], v[142:143] op_sel_hi:[1,0]
	s_mov_b32 vcc_lo, 0x8080808
	v_pk_mul_f32 v[56:57], v[56:57], v[142:143] op_sel_hi:[1,0]
	v_pk_mul_f32 v[58:59], v[58:59], v[142:143] op_sel_hi:[1,0]
	s_mov_b32 vcc_hi, 0x8080808
	v_pk_fma_f32 v[64:65], v[64:65], v[0:1], v[68:69] op_sel_hi:[1,0,1] neg_lo:[0,0,1] neg_hi:[0,0,1]
	v_pk_fma_f32 v[66:67], v[66:67], v[0:1], v[70:71] op_sel_hi:[1,0,1] neg_lo:[0,0,1] neg_hi:[0,0,1]
	v_cndmask_b32_e32 v134, v134, v143, vcc
	v_pk_fma_f32 v[60:61], v[60:61], v[0:1], v[56:57] op_sel_hi:[1,0,1] neg_lo:[0,0,1] neg_hi:[0,0,1]
	v_pk_fma_f32 v[62:63], v[62:63], v[0:1], v[58:59] op_sel_hi:[1,0,1] neg_lo:[0,0,1] neg_hi:[0,0,1]
	ds_read_b128 v[202:205], v124 offset:8720
	ds_read_b128 v[198:201], v124 offset:8704
	v_pk_fma_f32 v[36:37], v[36:37], v[48:49], v[64:65]
	v_pk_fma_f32 v[38:39], v[38:39], v[50:51], v[66:67]
	v_pk_fma_f32 v[32:33], v[32:33], v[40:41], v[60:61]
	v_pk_fma_f32 v[34:35], v[34:35], v[42:43], v[62:63]
	s_waitcnt lgkmcnt(2)
	v_pk_mul_f32 v[156:157], v[32:33], v[156:157]
	v_pk_mul_f32 v[52:53], v[32:33], v[52:53]
	v_pk_mul_f32 v[158:159], v[34:35], v[158:159]
	v_pk_mul_f32 v[54:55], v[34:35], v[54:55]
	v_pk_fma_f32 v[152:153], v[36:37], v[152:153], v[156:157]
	v_pk_fma_f32 v[44:45], v[36:37], v[44:45], v[52:53]
	v_pk_fma_f32 v[154:155], v[38:39], v[154:155], v[158:159]
	v_pk_fma_f32 v[46:47], v[38:39], v[46:47], v[54:55]
	v_pk_add_f32 v[152:153], v[152:153], v[154:155]
	v_pk_add_f32 v[44:45], v[44:45], v[46:47]
	v_add_f32_e32 v142, v152, v153
	v_add_f32_e32 v143, v44, v45
	ds_read_b128 v[76:79], v124 offset:9488
	v_add_f32_dpp v142, v142, v142 quad_perm:[1,0,3,2] row_mask:0xf bank_mask:0xf bound_ctrl:1
	v_add_f32_dpp v143, v143, v143 quad_perm:[1,0,3,2] row_mask:0xf bank_mask:0xf bound_ctrl:1
	ds_read_b128 v[72:75], v124 offset:9472
	v_add_f32_dpp v142, v142, v142 quad_perm:[2,3,0,1] row_mask:0xf bank_mask:0xf bound_ctrl:1
	v_add_f32_dpp v143, v143, v143 quad_perm:[2,3,0,1] row_mask:0xf bank_mask:0xf bound_ctrl:1
	ds_read_b128 v[68:71], v124 offset:9728
	v_add_f32_dpp v142, v142, v142 row_half_mirror row_mask:0xf bank_mask:0xf bound_ctrl:1
	v_add_f32_dpp v143, v143, v143 row_half_mirror row_mask:0xf bank_mask:0xf bound_ctrl:1
	ds_read_b128 v[56:59], v124 offset:9744
	ds_read_b32 v0, v135 offset:10496
	ds_read_b128 v[64:67], v124 offset:9984
	ds_read_b128 v[60:63], v124 offset:10000
	ds_read_b128 v[48:51], v124 offset:9216
	ds_read_b128 v[40:43], v124 offset:9232
	v_pk_mul_f32 v[182:183], v[182:183], v[142:143] op_sel_hi:[1,0]
	v_pk_mul_f32 v[184:185], v[184:185], v[142:143] op_sel_hi:[1,0]
	s_mov_b32 vcc_lo, 0x10101010
	v_pk_mul_f32 v[186:187], v[186:187], v[142:143] op_sel_hi:[1,0]
	v_pk_mul_f32 v[188:189], v[188:189], v[142:143] op_sel_hi:[1,0]
	s_mov_b32 vcc_hi, 0x10101010
	v_pk_fma_f32 v[190:191], v[190:191], v[160:161], v[182:183] op_sel_hi:[1,0,1] neg_lo:[0,0,1] neg_hi:[0,0,1]
	v_pk_fma_f32 v[192:193], v[192:193], v[160:161], v[184:185] op_sel_hi:[1,0,1] neg_lo:[0,0,1] neg_hi:[0,0,1]
	v_cndmask_b32_e32 v134, v134, v143, vcc
	v_pk_fma_f32 v[194:195], v[194:195], v[160:161], v[186:187] op_sel_hi:[1,0,1] neg_lo:[0,0,1] neg_hi:[0,0,1]
	v_pk_fma_f32 v[196:197], v[196:197], v[160:161], v[188:189] op_sel_hi:[1,0,1] neg_lo:[0,0,1] neg_hi:[0,0,1]
	ds_read_b128 v[52:55], v124 offset:10256
	ds_read_b128 v[44:47], v124 offset:10240
	v_pk_fma_f32 v[36:37], v[36:37], v[144:145], v[190:191]
	v_pk_fma_f32 v[38:39], v[38:39], v[146:147], v[192:193]
	v_pk_fma_f32 v[32:33], v[32:33], v[148:149], v[194:195]
	v_pk_fma_f32 v[34:35], v[34:35], v[150:151], v[196:197]
	s_waitcnt lgkmcnt(2)
	v_pk_mul_f32 v[76:77], v[32:33], v[76:77]
	v_pk_mul_f32 v[202:203], v[32:33], v[202:203]
	v_pk_mul_f32 v[78:79], v[34:35], v[78:79]
	v_pk_mul_f32 v[204:205], v[34:35], v[204:205]
	v_pk_fma_f32 v[72:73], v[36:37], v[72:73], v[76:77]
	v_pk_fma_f32 v[198:199], v[36:37], v[198:199], v[202:203]
	v_pk_fma_f32 v[74:75], v[38:39], v[74:75], v[78:79]
	v_pk_fma_f32 v[200:201], v[38:39], v[200:201], v[204:205]
	v_pk_add_f32 v[72:73], v[72:73], v[74:75]
	v_pk_add_f32 v[198:199], v[198:199], v[200:201]
	v_add_f32_e32 v142, v72, v73
	v_add_f32_e32 v143, v198, v199
	ds_read_b128 v[156:159], v124 offset:11024
	v_add_f32_dpp v142, v142, v142 quad_perm:[1,0,3,2] row_mask:0xf bank_mask:0xf bound_ctrl:1
	v_add_f32_dpp v143, v143, v143 quad_perm:[1,0,3,2] row_mask:0xf bank_mask:0xf bound_ctrl:1
	ds_read_b128 v[152:155], v124 offset:11008
	v_add_f32_dpp v142, v142, v142 quad_perm:[2,3,0,1] row_mask:0xf bank_mask:0xf bound_ctrl:1
	v_add_f32_dpp v143, v143, v143 quad_perm:[2,3,0,1] row_mask:0xf bank_mask:0xf bound_ctrl:1
	ds_read_b128 v[182:185], v124 offset:11264
	v_add_f32_dpp v142, v142, v142 row_half_mirror row_mask:0xf bank_mask:0xf bound_ctrl:1
	v_add_f32_dpp v143, v143, v143 row_half_mirror row_mask:0xf bank_mask:0xf bound_ctrl:1
	ds_read_b128 v[186:189], v124 offset:11280
	ds_read_b32 v160, v135 offset:12032
	ds_read_b128 v[190:193], v124 offset:11520
	ds_read_b128 v[194:197], v124 offset:11536
	ds_read_b128 v[144:147], v124 offset:10752
	ds_read_b128 v[148:151], v124 offset:10768
	v_pk_mul_f32 v[68:69], v[68:69], v[142:143] op_sel_hi:[1,0]
	v_pk_mul_f32 v[70:71], v[70:71], v[142:143] op_sel_hi:[1,0]
	s_mov_b32 vcc_lo, 0x20202020
	v_pk_mul_f32 v[56:57], v[56:57], v[142:143] op_sel_hi:[1,0]
	v_pk_mul_f32 v[58:59], v[58:59], v[142:143] op_sel_hi:[1,0]
	s_mov_b32 vcc_hi, 0x20202020
	v_pk_fma_f32 v[64:65], v[64:65], v[0:1], v[68:69] op_sel_hi:[1,0,1] neg_lo:[0,0,1] neg_hi:[0,0,1]
	v_pk_fma_f32 v[66:67], v[66:67], v[0:1], v[70:71] op_sel_hi:[1,0,1] neg_lo:[0,0,1] neg_hi:[0,0,1]
	v_cndmask_b32_e32 v134, v134, v143, vcc
	v_pk_fma_f32 v[60:61], v[60:61], v[0:1], v[56:57] op_sel_hi:[1,0,1] neg_lo:[0,0,1] neg_hi:[0,0,1]
	v_pk_fma_f32 v[62:63], v[62:63], v[0:1], v[58:59] op_sel_hi:[1,0,1] neg_lo:[0,0,1] neg_hi:[0,0,1]
	ds_read_b128 v[202:205], v124 offset:11792
	ds_read_b128 v[198:201], v124 offset:11776
	v_pk_fma_f32 v[36:37], v[36:37], v[48:49], v[64:65]
	v_pk_fma_f32 v[38:39], v[38:39], v[50:51], v[66:67]
	v_pk_fma_f32 v[32:33], v[32:33], v[40:41], v[60:61]
	v_pk_fma_f32 v[34:35], v[34:35], v[42:43], v[62:63]
	s_waitcnt lgkmcnt(2)
	v_pk_mul_f32 v[156:157], v[32:33], v[156:157]
	v_pk_mul_f32 v[52:53], v[32:33], v[52:53]
	v_pk_mul_f32 v[158:159], v[34:35], v[158:159]
	v_pk_mul_f32 v[54:55], v[34:35], v[54:55]
	v_pk_fma_f32 v[152:153], v[36:37], v[152:153], v[156:157]
	v_pk_fma_f32 v[44:45], v[36:37], v[44:45], v[52:53]
	v_pk_fma_f32 v[154:155], v[38:39], v[154:155], v[158:159]
	v_pk_fma_f32 v[46:47], v[38:39], v[46:47], v[54:55]
	v_pk_add_f32 v[152:153], v[152:153], v[154:155]
	v_pk_add_f32 v[44:45], v[44:45], v[46:47]
	v_add_f32_e32 v142, v152, v153
	v_add_f32_e32 v143, v44, v45
	ds_read_b128 v[76:79], v124 offset:12560
	v_add_f32_dpp v142, v142, v142 quad_perm:[1,0,3,2] row_mask:0xf bank_mask:0xf bound_ctrl:1
	v_add_f32_dpp v143, v143, v143 quad_perm:[1,0,3,2] row_mask:0xf bank_mask:0xf bound_ctrl:1
	ds_read_b128 v[72:75], v124 offset:12544
	v_add_f32_dpp v142, v142, v142 quad_perm:[2,3,0,1] row_mask:0xf bank_mask:0xf bound_ctrl:1
	v_add_f32_dpp v143, v143, v143 quad_perm:[2,3,0,1] row_mask:0xf bank_mask:0xf bound_ctrl:1
	ds_read_b128 v[68:71], v124 offset:12800
	v_add_f32_dpp v142, v142, v142 row_half_mirror row_mask:0xf bank_mask:0xf bound_ctrl:1
	v_add_f32_dpp v143, v143, v143 row_half_mirror row_mask:0xf bank_mask:0xf bound_ctrl:1
	ds_read_b128 v[56:59], v124 offset:12816
	ds_read_b32 v0, v135 offset:13568
	ds_read_b128 v[64:67], v124 offset:13056
	ds_read_b128 v[60:63], v124 offset:13072
	ds_read_b128 v[48:51], v124 offset:12288
	ds_read_b128 v[40:43], v124 offset:12304
	v_pk_mul_f32 v[182:183], v[182:183], v[142:143] op_sel_hi:[1,0]
	v_pk_mul_f32 v[184:185], v[184:185], v[142:143] op_sel_hi:[1,0]
	s_mov_b32 vcc_lo, 0x40404040
	v_pk_mul_f32 v[186:187], v[186:187], v[142:143] op_sel_hi:[1,0]
	v_pk_mul_f32 v[188:189], v[188:189], v[142:143] op_sel_hi:[1,0]
	s_mov_b32 vcc_hi, 0x40404040
	v_pk_fma_f32 v[190:191], v[190:191], v[160:161], v[182:183] op_sel_hi:[1,0,1] neg_lo:[0,0,1] neg_hi:[0,0,1]
	v_pk_fma_f32 v[192:193], v[192:193], v[160:161], v[184:185] op_sel_hi:[1,0,1] neg_lo:[0,0,1] neg_hi:[0,0,1]
	v_cndmask_b32_e32 v134, v134, v143, vcc
	v_pk_fma_f32 v[194:195], v[194:195], v[160:161], v[186:187] op_sel_hi:[1,0,1] neg_lo:[0,0,1] neg_hi:[0,0,1]
	v_pk_fma_f32 v[196:197], v[196:197], v[160:161], v[188:189] op_sel_hi:[1,0,1] neg_lo:[0,0,1] neg_hi:[0,0,1]
	ds_read_b128 v[52:55], v124 offset:13328
	ds_read_b128 v[44:47], v124 offset:13312
	v_pk_fma_f32 v[36:37], v[36:37], v[144:145], v[190:191]
	v_pk_fma_f32 v[38:39], v[38:39], v[146:147], v[192:193]
	v_pk_fma_f32 v[32:33], v[32:33], v[148:149], v[194:195]
	v_pk_fma_f32 v[34:35], v[34:35], v[150:151], v[196:197]
	s_waitcnt lgkmcnt(2)
	v_pk_mul_f32 v[76:77], v[32:33], v[76:77]
	v_pk_mul_f32 v[202:203], v[32:33], v[202:203]
	v_pk_mul_f32 v[78:79], v[34:35], v[78:79]
	v_pk_mul_f32 v[204:205], v[34:35], v[204:205]
	v_pk_fma_f32 v[72:73], v[36:37], v[72:73], v[76:77]
	v_pk_fma_f32 v[198:199], v[36:37], v[198:199], v[202:203]
	v_pk_fma_f32 v[74:75], v[38:39], v[74:75], v[78:79]
	v_pk_fma_f32 v[200:201], v[38:39], v[200:201], v[204:205]
	v_pk_add_f32 v[72:73], v[72:73], v[74:75]
	v_pk_add_f32 v[198:199], v[198:199], v[200:201]
	v_add_f32_e32 v142, v72, v73
	v_add_f32_e32 v143, v198, v199
	ds_read_b128 v[156:159], v124 offset:14096
	v_add_f32_dpp v142, v142, v142 quad_perm:[1,0,3,2] row_mask:0xf bank_mask:0xf bound_ctrl:1
	v_add_f32_dpp v143, v143, v143 quad_perm:[1,0,3,2] row_mask:0xf bank_mask:0xf bound_ctrl:1
	ds_read_b128 v[152:155], v124 offset:14080
	v_add_f32_dpp v142, v142, v142 quad_perm:[2,3,0,1] row_mask:0xf bank_mask:0xf bound_ctrl:1
	v_add_f32_dpp v143, v143, v143 quad_perm:[2,3,0,1] row_mask:0xf bank_mask:0xf bound_ctrl:1
	ds_read_b128 v[182:185], v124 offset:14336
	v_add_f32_dpp v142, v142, v142 row_half_mirror row_mask:0xf bank_mask:0xf bound_ctrl:1
	v_add_f32_dpp v143, v143, v143 row_half_mirror row_mask:0xf bank_mask:0xf bound_ctrl:1
	ds_read_b128 v[186:189], v124 offset:14352
	ds_read_b32 v160, v135 offset:15104
	ds_read_b128 v[190:193], v124 offset:14592
	ds_read_b128 v[194:197], v124 offset:14608
	ds_read_b128 v[144:147], v124 offset:13824
	ds_read_b128 v[148:151], v124 offset:13840
	v_pk_mul_f32 v[68:69], v[68:69], v[142:143] op_sel_hi:[1,0]
	v_pk_mul_f32 v[70:71], v[70:71], v[142:143] op_sel_hi:[1,0]
	s_mov_b32 vcc_lo, 0x80808080
	v_pk_mul_f32 v[56:57], v[56:57], v[142:143] op_sel_hi:[1,0]
	v_pk_mul_f32 v[58:59], v[58:59], v[142:143] op_sel_hi:[1,0]
	s_mov_b32 vcc_hi, 0x80808080
	v_pk_fma_f32 v[64:65], v[64:65], v[0:1], v[68:69] op_sel_hi:[1,0,1] neg_lo:[0,0,1] neg_hi:[0,0,1]
	v_pk_fma_f32 v[66:67], v[66:67], v[0:1], v[70:71] op_sel_hi:[1,0,1] neg_lo:[0,0,1] neg_hi:[0,0,1]
	v_cndmask_b32_e32 v134, v134, v143, vcc
	v_pk_fma_f32 v[60:61], v[60:61], v[0:1], v[56:57] op_sel_hi:[1,0,1] neg_lo:[0,0,1] neg_hi:[0,0,1]
	v_pk_fma_f32 v[62:63], v[62:63], v[0:1], v[58:59] op_sel_hi:[1,0,1] neg_lo:[0,0,1] neg_hi:[0,0,1]
	ds_read_b128 v[202:205], v124 offset:14864
	ds_read_b128 v[198:201], v124 offset:14848
	v_pk_fma_f32 v[36:37], v[36:37], v[48:49], v[64:65]
	v_pk_fma_f32 v[38:39], v[38:39], v[50:51], v[66:67]
	v_pk_fma_f32 v[32:33], v[32:33], v[40:41], v[60:61]
	v_pk_fma_f32 v[34:35], v[34:35], v[42:43], v[62:63]
	s_waitcnt lgkmcnt(2)
	v_pk_mul_f32 v[156:157], v[32:33], v[156:157]
	v_pk_mul_f32 v[52:53], v[32:33], v[52:53]
	v_pk_mul_f32 v[158:159], v[34:35], v[158:159]
	v_pk_mul_f32 v[54:55], v[34:35], v[54:55]
	v_pk_fma_f32 v[152:153], v[36:37], v[152:153], v[156:157]
	v_pk_fma_f32 v[44:45], v[36:37], v[44:45], v[52:53]
	v_pk_fma_f32 v[154:155], v[38:39], v[154:155], v[158:159]
	v_pk_fma_f32 v[46:47], v[38:39], v[46:47], v[54:55]
	v_pk_add_f32 v[152:153], v[152:153], v[154:155]
	v_pk_add_f32 v[44:45], v[44:45], v[46:47]
	v_add_f32_e32 v142, v152, v153
	v_add_f32_e32 v143, v44, v45
	ds_read_b128 v[76:79], v124 offset:15632
	v_add_f32_dpp v142, v142, v142 quad_perm:[1,0,3,2] row_mask:0xf bank_mask:0xf bound_ctrl:1
	v_add_f32_dpp v143, v143, v143 quad_perm:[1,0,3,2] row_mask:0xf bank_mask:0xf bound_ctrl:1
	ds_read_b128 v[72:75], v124 offset:15616
	v_add_f32_dpp v142, v142, v142 quad_perm:[2,3,0,1] row_mask:0xf bank_mask:0xf bound_ctrl:1
	v_add_f32_dpp v143, v143, v143 quad_perm:[2,3,0,1] row_mask:0xf bank_mask:0xf bound_ctrl:1
	ds_read_b128 v[68:71], v124 offset:15872
	v_add_f32_dpp v142, v142, v142 row_half_mirror row_mask:0xf bank_mask:0xf bound_ctrl:1
	v_add_f32_dpp v143, v143, v143 row_half_mirror row_mask:0xf bank_mask:0xf bound_ctrl:1
	ds_read_b128 v[56:59], v124 offset:15888
	ds_read_b32 v0, v135 offset:16640
	ds_read_b128 v[64:67], v124 offset:16128
	ds_read_b128 v[60:63], v124 offset:16144
	ds_read_b128 v[48:51], v124 offset:15360
	ds_read_b128 v[40:43], v124 offset:15376
	v_pk_mul_f32 v[182:183], v[182:183], v[142:143] op_sel_hi:[1,0]
	v_pk_mul_f32 v[184:185], v[184:185], v[142:143] op_sel_hi:[1,0]
	s_mov_b32 vcc_lo, 0x1010101
	v_pk_mul_f32 v[186:187], v[186:187], v[142:143] op_sel_hi:[1,0]
	v_pk_mul_f32 v[188:189], v[188:189], v[142:143] op_sel_hi:[1,0]
	s_mov_b32 vcc_hi, 0x1010101
	v_pk_fma_f32 v[190:191], v[190:191], v[160:161], v[182:183] op_sel_hi:[1,0,1] neg_lo:[0,0,1] neg_hi:[0,0,1]
	v_pk_fma_f32 v[192:193], v[192:193], v[160:161], v[184:185] op_sel_hi:[1,0,1] neg_lo:[0,0,1] neg_hi:[0,0,1]
	v_cndmask_b32_e32 v133, v133, v143, vcc
	v_pk_fma_f32 v[194:195], v[194:195], v[160:161], v[186:187] op_sel_hi:[1,0,1] neg_lo:[0,0,1] neg_hi:[0,0,1]
	v_pk_fma_f32 v[196:197], v[196:197], v[160:161], v[188:189] op_sel_hi:[1,0,1] neg_lo:[0,0,1] neg_hi:[0,0,1]
	ds_read_b128 v[52:55], v124 offset:16400
	ds_read_b128 v[44:47], v124 offset:16384
	v_pk_fma_f32 v[36:37], v[36:37], v[144:145], v[190:191]
	v_pk_fma_f32 v[38:39], v[38:39], v[146:147], v[192:193]
	v_pk_fma_f32 v[32:33], v[32:33], v[148:149], v[194:195]
	v_pk_fma_f32 v[34:35], v[34:35], v[150:151], v[196:197]
	s_waitcnt lgkmcnt(2)
	v_pk_mul_f32 v[76:77], v[32:33], v[76:77]
	v_pk_mul_f32 v[202:203], v[32:33], v[202:203]
	v_pk_mul_f32 v[78:79], v[34:35], v[78:79]
	v_pk_mul_f32 v[204:205], v[34:35], v[204:205]
	v_pk_fma_f32 v[72:73], v[36:37], v[72:73], v[76:77]
	v_pk_fma_f32 v[198:199], v[36:37], v[198:199], v[202:203]
	v_pk_fma_f32 v[74:75], v[38:39], v[74:75], v[78:79]
	v_pk_fma_f32 v[200:201], v[38:39], v[200:201], v[204:205]
	v_pk_add_f32 v[72:73], v[72:73], v[74:75]
	v_pk_add_f32 v[198:199], v[198:199], v[200:201]
	v_add_f32_e32 v142, v72, v73
	v_add_f32_e32 v143, v198, v199
	ds_read_b128 v[156:159], v124 offset:17168
	v_add_f32_dpp v142, v142, v142 quad_perm:[1,0,3,2] row_mask:0xf bank_mask:0xf bound_ctrl:1
	v_add_f32_dpp v143, v143, v143 quad_perm:[1,0,3,2] row_mask:0xf bank_mask:0xf bound_ctrl:1
	ds_read_b128 v[152:155], v124 offset:17152
	v_add_f32_dpp v142, v142, v142 quad_perm:[2,3,0,1] row_mask:0xf bank_mask:0xf bound_ctrl:1
	v_add_f32_dpp v143, v143, v143 quad_perm:[2,3,0,1] row_mask:0xf bank_mask:0xf bound_ctrl:1
	ds_read_b128 v[182:185], v124 offset:17408
	v_add_f32_dpp v142, v142, v142 row_half_mirror row_mask:0xf bank_mask:0xf bound_ctrl:1
	v_add_f32_dpp v143, v143, v143 row_half_mirror row_mask:0xf bank_mask:0xf bound_ctrl:1
	ds_read_b128 v[186:189], v124 offset:17424
	ds_read_b32 v160, v135 offset:18176
	ds_read_b128 v[190:193], v124 offset:17664
	ds_read_b128 v[194:197], v124 offset:17680
	ds_read_b128 v[144:147], v124 offset:16896
	ds_read_b128 v[148:151], v124 offset:16912
	v_pk_mul_f32 v[68:69], v[68:69], v[142:143] op_sel_hi:[1,0]
	v_pk_mul_f32 v[70:71], v[70:71], v[142:143] op_sel_hi:[1,0]
	s_mov_b32 vcc_lo, 0x2020202
	v_pk_mul_f32 v[56:57], v[56:57], v[142:143] op_sel_hi:[1,0]
	v_pk_mul_f32 v[58:59], v[58:59], v[142:143] op_sel_hi:[1,0]
	s_mov_b32 vcc_hi, 0x2020202
	v_pk_fma_f32 v[64:65], v[64:65], v[0:1], v[68:69] op_sel_hi:[1,0,1] neg_lo:[0,0,1] neg_hi:[0,0,1]
	v_pk_fma_f32 v[66:67], v[66:67], v[0:1], v[70:71] op_sel_hi:[1,0,1] neg_lo:[0,0,1] neg_hi:[0,0,1]
	v_cndmask_b32_e32 v133, v133, v143, vcc
	v_pk_fma_f32 v[60:61], v[60:61], v[0:1], v[56:57] op_sel_hi:[1,0,1] neg_lo:[0,0,1] neg_hi:[0,0,1]
	v_pk_fma_f32 v[62:63], v[62:63], v[0:1], v[58:59] op_sel_hi:[1,0,1] neg_lo:[0,0,1] neg_hi:[0,0,1]
	ds_read_b128 v[202:205], v124 offset:17936
	ds_read_b128 v[198:201], v124 offset:17920
	v_pk_fma_f32 v[36:37], v[36:37], v[48:49], v[64:65]
	v_pk_fma_f32 v[38:39], v[38:39], v[50:51], v[66:67]
	v_pk_fma_f32 v[32:33], v[32:33], v[40:41], v[60:61]
	v_pk_fma_f32 v[34:35], v[34:35], v[42:43], v[62:63]
	s_waitcnt lgkmcnt(2)
	v_pk_mul_f32 v[156:157], v[32:33], v[156:157]
	v_pk_mul_f32 v[52:53], v[32:33], v[52:53]
	v_pk_mul_f32 v[158:159], v[34:35], v[158:159]
	v_pk_mul_f32 v[54:55], v[34:35], v[54:55]
	v_pk_fma_f32 v[152:153], v[36:37], v[152:153], v[156:157]
	v_pk_fma_f32 v[44:45], v[36:37], v[44:45], v[52:53]
	v_pk_fma_f32 v[154:155], v[38:39], v[154:155], v[158:159]
	v_pk_fma_f32 v[46:47], v[38:39], v[46:47], v[54:55]
	v_pk_add_f32 v[152:153], v[152:153], v[154:155]
	v_pk_add_f32 v[44:45], v[44:45], v[46:47]
	v_add_f32_e32 v142, v152, v153
	v_add_f32_e32 v143, v44, v45
	ds_read_b128 v[76:79], v124 offset:18704
	v_add_f32_dpp v142, v142, v142 quad_perm:[1,0,3,2] row_mask:0xf bank_mask:0xf bound_ctrl:1
	v_add_f32_dpp v143, v143, v143 quad_perm:[1,0,3,2] row_mask:0xf bank_mask:0xf bound_ctrl:1
	ds_read_b128 v[72:75], v124 offset:18688
	v_add_f32_dpp v142, v142, v142 quad_perm:[2,3,0,1] row_mask:0xf bank_mask:0xf bound_ctrl:1
	v_add_f32_dpp v143, v143, v143 quad_perm:[2,3,0,1] row_mask:0xf bank_mask:0xf bound_ctrl:1
	ds_read_b128 v[68:71], v124 offset:18944
	v_add_f32_dpp v142, v142, v142 row_half_mirror row_mask:0xf bank_mask:0xf bound_ctrl:1
	v_add_f32_dpp v143, v143, v143 row_half_mirror row_mask:0xf bank_mask:0xf bound_ctrl:1
	ds_read_b128 v[56:59], v124 offset:18960
	ds_read_b32 v0, v135 offset:19712
	ds_read_b128 v[64:67], v124 offset:19200
	ds_read_b128 v[60:63], v124 offset:19216
	ds_read_b128 v[48:51], v124 offset:18432
	ds_read_b128 v[40:43], v124 offset:18448
	v_pk_mul_f32 v[182:183], v[182:183], v[142:143] op_sel_hi:[1,0]
	v_pk_mul_f32 v[184:185], v[184:185], v[142:143] op_sel_hi:[1,0]
	s_mov_b32 vcc_lo, 0x4040404
	v_pk_mul_f32 v[186:187], v[186:187], v[142:143] op_sel_hi:[1,0]
	v_pk_mul_f32 v[188:189], v[188:189], v[142:143] op_sel_hi:[1,0]
	s_mov_b32 vcc_hi, 0x4040404
	v_pk_fma_f32 v[190:191], v[190:191], v[160:161], v[182:183] op_sel_hi:[1,0,1] neg_lo:[0,0,1] neg_hi:[0,0,1]
	v_pk_fma_f32 v[192:193], v[192:193], v[160:161], v[184:185] op_sel_hi:[1,0,1] neg_lo:[0,0,1] neg_hi:[0,0,1]
	v_cndmask_b32_e32 v133, v133, v143, vcc
	v_pk_fma_f32 v[194:195], v[194:195], v[160:161], v[186:187] op_sel_hi:[1,0,1] neg_lo:[0,0,1] neg_hi:[0,0,1]
	v_pk_fma_f32 v[196:197], v[196:197], v[160:161], v[188:189] op_sel_hi:[1,0,1] neg_lo:[0,0,1] neg_hi:[0,0,1]
	ds_read_b128 v[52:55], v124 offset:19472
	ds_read_b128 v[44:47], v124 offset:19456
	v_pk_fma_f32 v[36:37], v[36:37], v[144:145], v[190:191]
	v_pk_fma_f32 v[38:39], v[38:39], v[146:147], v[192:193]
	v_pk_fma_f32 v[32:33], v[32:33], v[148:149], v[194:195]
	v_pk_fma_f32 v[34:35], v[34:35], v[150:151], v[196:197]
	s_waitcnt lgkmcnt(2)
	v_pk_mul_f32 v[76:77], v[32:33], v[76:77]
	v_pk_mul_f32 v[202:203], v[32:33], v[202:203]
	v_pk_mul_f32 v[78:79], v[34:35], v[78:79]
	v_pk_mul_f32 v[204:205], v[34:35], v[204:205]
	v_pk_fma_f32 v[72:73], v[36:37], v[72:73], v[76:77]
	v_pk_fma_f32 v[198:199], v[36:37], v[198:199], v[202:203]
	v_pk_fma_f32 v[74:75], v[38:39], v[74:75], v[78:79]
	v_pk_fma_f32 v[200:201], v[38:39], v[200:201], v[204:205]
	v_pk_add_f32 v[72:73], v[72:73], v[74:75]
	v_pk_add_f32 v[198:199], v[198:199], v[200:201]
	v_add_f32_e32 v142, v72, v73
	v_add_f32_e32 v143, v198, v199
	ds_read_b128 v[156:159], v124 offset:20240
	v_add_f32_dpp v142, v142, v142 quad_perm:[1,0,3,2] row_mask:0xf bank_mask:0xf bound_ctrl:1
	v_add_f32_dpp v143, v143, v143 quad_perm:[1,0,3,2] row_mask:0xf bank_mask:0xf bound_ctrl:1
	ds_read_b128 v[152:155], v124 offset:20224
	v_add_f32_dpp v142, v142, v142 quad_perm:[2,3,0,1] row_mask:0xf bank_mask:0xf bound_ctrl:1
	v_add_f32_dpp v143, v143, v143 quad_perm:[2,3,0,1] row_mask:0xf bank_mask:0xf bound_ctrl:1
	ds_read_b128 v[182:185], v124 offset:20480
	v_add_f32_dpp v142, v142, v142 row_half_mirror row_mask:0xf bank_mask:0xf bound_ctrl:1
	v_add_f32_dpp v143, v143, v143 row_half_mirror row_mask:0xf bank_mask:0xf bound_ctrl:1
	ds_read_b128 v[186:189], v124 offset:20496
	ds_read_b32 v160, v135 offset:21248
	ds_read_b128 v[190:193], v124 offset:20736
	ds_read_b128 v[194:197], v124 offset:20752
	ds_read_b128 v[144:147], v124 offset:19968
	ds_read_b128 v[148:151], v124 offset:19984
	v_pk_mul_f32 v[68:69], v[68:69], v[142:143] op_sel_hi:[1,0]
	v_pk_mul_f32 v[70:71], v[70:71], v[142:143] op_sel_hi:[1,0]
	s_mov_b32 vcc_lo, 0x8080808
	v_pk_mul_f32 v[56:57], v[56:57], v[142:143] op_sel_hi:[1,0]
	v_pk_mul_f32 v[58:59], v[58:59], v[142:143] op_sel_hi:[1,0]
	s_mov_b32 vcc_hi, 0x8080808
	v_pk_fma_f32 v[64:65], v[64:65], v[0:1], v[68:69] op_sel_hi:[1,0,1] neg_lo:[0,0,1] neg_hi:[0,0,1]
	v_pk_fma_f32 v[66:67], v[66:67], v[0:1], v[70:71] op_sel_hi:[1,0,1] neg_lo:[0,0,1] neg_hi:[0,0,1]
	v_cndmask_b32_e32 v133, v133, v143, vcc
	v_pk_fma_f32 v[60:61], v[60:61], v[0:1], v[56:57] op_sel_hi:[1,0,1] neg_lo:[0,0,1] neg_hi:[0,0,1]
	v_pk_fma_f32 v[62:63], v[62:63], v[0:1], v[58:59] op_sel_hi:[1,0,1] neg_lo:[0,0,1] neg_hi:[0,0,1]
	ds_read_b128 v[202:205], v124 offset:21008
	ds_read_b128 v[198:201], v124 offset:20992
	v_pk_fma_f32 v[36:37], v[36:37], v[48:49], v[64:65]
	v_pk_fma_f32 v[38:39], v[38:39], v[50:51], v[66:67]
	v_pk_fma_f32 v[32:33], v[32:33], v[40:41], v[60:61]
	v_pk_fma_f32 v[34:35], v[34:35], v[42:43], v[62:63]
	s_waitcnt lgkmcnt(2)
	v_pk_mul_f32 v[156:157], v[32:33], v[156:157]
	v_pk_mul_f32 v[52:53], v[32:33], v[52:53]
	v_pk_mul_f32 v[158:159], v[34:35], v[158:159]
	v_pk_mul_f32 v[54:55], v[34:35], v[54:55]
	v_pk_fma_f32 v[152:153], v[36:37], v[152:153], v[156:157]
	v_pk_fma_f32 v[44:45], v[36:37], v[44:45], v[52:53]
	v_pk_fma_f32 v[154:155], v[38:39], v[154:155], v[158:159]
	v_pk_fma_f32 v[46:47], v[38:39], v[46:47], v[54:55]
	v_pk_add_f32 v[152:153], v[152:153], v[154:155]
	v_pk_add_f32 v[44:45], v[44:45], v[46:47]
	v_add_f32_e32 v142, v152, v153
	v_add_f32_e32 v143, v44, v45
	ds_read_b128 v[76:79], v124 offset:21776
	v_add_f32_dpp v142, v142, v142 quad_perm:[1,0,3,2] row_mask:0xf bank_mask:0xf bound_ctrl:1
	v_add_f32_dpp v143, v143, v143 quad_perm:[1,0,3,2] row_mask:0xf bank_mask:0xf bound_ctrl:1
	ds_read_b128 v[72:75], v124 offset:21760
	v_add_f32_dpp v142, v142, v142 quad_perm:[2,3,0,1] row_mask:0xf bank_mask:0xf bound_ctrl:1
	v_add_f32_dpp v143, v143, v143 quad_perm:[2,3,0,1] row_mask:0xf bank_mask:0xf bound_ctrl:1
	ds_read_b128 v[68:71], v124 offset:22016
	v_add_f32_dpp v142, v142, v142 row_half_mirror row_mask:0xf bank_mask:0xf bound_ctrl:1
	v_add_f32_dpp v143, v143, v143 row_half_mirror row_mask:0xf bank_mask:0xf bound_ctrl:1
	ds_read_b128 v[56:59], v124 offset:22032
	ds_read_b32 v0, v135 offset:22784
	ds_read_b128 v[64:67], v124 offset:22272
	ds_read_b128 v[60:63], v124 offset:22288
	ds_read_b128 v[48:51], v124 offset:21504
	ds_read_b128 v[40:43], v124 offset:21520
	v_pk_mul_f32 v[182:183], v[182:183], v[142:143] op_sel_hi:[1,0]
	v_pk_mul_f32 v[184:185], v[184:185], v[142:143] op_sel_hi:[1,0]
	s_mov_b32 vcc_lo, 0x10101010
	v_pk_mul_f32 v[186:187], v[186:187], v[142:143] op_sel_hi:[1,0]
	v_pk_mul_f32 v[188:189], v[188:189], v[142:143] op_sel_hi:[1,0]
	s_mov_b32 vcc_hi, 0x10101010
	v_pk_fma_f32 v[190:191], v[190:191], v[160:161], v[182:183] op_sel_hi:[1,0,1] neg_lo:[0,0,1] neg_hi:[0,0,1]
	v_pk_fma_f32 v[192:193], v[192:193], v[160:161], v[184:185] op_sel_hi:[1,0,1] neg_lo:[0,0,1] neg_hi:[0,0,1]
	v_cndmask_b32_e32 v133, v133, v143, vcc
	v_pk_fma_f32 v[194:195], v[194:195], v[160:161], v[186:187] op_sel_hi:[1,0,1] neg_lo:[0,0,1] neg_hi:[0,0,1]
	v_pk_fma_f32 v[196:197], v[196:197], v[160:161], v[188:189] op_sel_hi:[1,0,1] neg_lo:[0,0,1] neg_hi:[0,0,1]
	ds_read_b128 v[52:55], v124 offset:22544
	ds_read_b128 v[44:47], v124 offset:22528
	v_pk_fma_f32 v[36:37], v[36:37], v[144:145], v[190:191]
	v_pk_fma_f32 v[38:39], v[38:39], v[146:147], v[192:193]
	v_pk_fma_f32 v[32:33], v[32:33], v[148:149], v[194:195]
	v_pk_fma_f32 v[34:35], v[34:35], v[150:151], v[196:197]
	s_waitcnt lgkmcnt(2)
	v_pk_mul_f32 v[76:77], v[32:33], v[76:77]
	v_pk_mul_f32 v[202:203], v[32:33], v[202:203]
	v_pk_mul_f32 v[78:79], v[34:35], v[78:79]
	v_pk_mul_f32 v[204:205], v[34:35], v[204:205]
	v_pk_fma_f32 v[72:73], v[36:37], v[72:73], v[76:77]
	v_pk_fma_f32 v[198:199], v[36:37], v[198:199], v[202:203]
	v_pk_fma_f32 v[74:75], v[38:39], v[74:75], v[78:79]
	v_pk_fma_f32 v[200:201], v[38:39], v[200:201], v[204:205]
	v_pk_add_f32 v[72:73], v[72:73], v[74:75]
	v_pk_add_f32 v[198:199], v[198:199], v[200:201]
	v_add_f32_e32 v142, v72, v73
	v_add_f32_e32 v143, v198, v199
	ds_read_b128 v[156:159], v124 offset:23312
	v_add_f32_dpp v142, v142, v142 quad_perm:[1,0,3,2] row_mask:0xf bank_mask:0xf bound_ctrl:1
	v_add_f32_dpp v143, v143, v143 quad_perm:[1,0,3,2] row_mask:0xf bank_mask:0xf bound_ctrl:1
	ds_read_b128 v[152:155], v124 offset:23296
	v_add_f32_dpp v142, v142, v142 quad_perm:[2,3,0,1] row_mask:0xf bank_mask:0xf bound_ctrl:1
	v_add_f32_dpp v143, v143, v143 quad_perm:[2,3,0,1] row_mask:0xf bank_mask:0xf bound_ctrl:1
	ds_read_b128 v[182:185], v124 offset:23552
	v_add_f32_dpp v142, v142, v142 row_half_mirror row_mask:0xf bank_mask:0xf bound_ctrl:1
	v_add_f32_dpp v143, v143, v143 row_half_mirror row_mask:0xf bank_mask:0xf bound_ctrl:1
	ds_read_b128 v[186:189], v124 offset:23568
	ds_read_b32 v160, v135 offset:24320
	ds_read_b128 v[190:193], v124 offset:23808
	ds_read_b128 v[194:197], v124 offset:23824
	ds_read_b128 v[144:147], v124 offset:23040
	ds_read_b128 v[148:151], v124 offset:23056
	v_pk_mul_f32 v[68:69], v[68:69], v[142:143] op_sel_hi:[1,0]
	v_pk_mul_f32 v[70:71], v[70:71], v[142:143] op_sel_hi:[1,0]
	s_mov_b32 vcc_lo, 0x20202020
	v_pk_mul_f32 v[56:57], v[56:57], v[142:143] op_sel_hi:[1,0]
	v_pk_mul_f32 v[58:59], v[58:59], v[142:143] op_sel_hi:[1,0]
	s_mov_b32 vcc_hi, 0x20202020
	v_pk_fma_f32 v[64:65], v[64:65], v[0:1], v[68:69] op_sel_hi:[1,0,1] neg_lo:[0,0,1] neg_hi:[0,0,1]
	v_pk_fma_f32 v[66:67], v[66:67], v[0:1], v[70:71] op_sel_hi:[1,0,1] neg_lo:[0,0,1] neg_hi:[0,0,1]
	v_cndmask_b32_e32 v133, v133, v143, vcc
	v_pk_fma_f32 v[60:61], v[60:61], v[0:1], v[56:57] op_sel_hi:[1,0,1] neg_lo:[0,0,1] neg_hi:[0,0,1]
	v_pk_fma_f32 v[62:63], v[62:63], v[0:1], v[58:59] op_sel_hi:[1,0,1] neg_lo:[0,0,1] neg_hi:[0,0,1]
	ds_read_b128 v[202:205], v124 offset:24080
	ds_read_b128 v[198:201], v124 offset:24064
	v_pk_fma_f32 v[36:37], v[36:37], v[48:49], v[64:65]
	v_pk_fma_f32 v[38:39], v[38:39], v[50:51], v[66:67]
	v_pk_fma_f32 v[32:33], v[32:33], v[40:41], v[60:61]
	v_pk_fma_f32 v[34:35], v[34:35], v[42:43], v[62:63]
	s_waitcnt lgkmcnt(2)
	v_pk_mul_f32 v[156:157], v[32:33], v[156:157]
	v_pk_mul_f32 v[52:53], v[32:33], v[52:53]
	v_pk_mul_f32 v[158:159], v[34:35], v[158:159]
	v_pk_mul_f32 v[54:55], v[34:35], v[54:55]
	v_pk_fma_f32 v[152:153], v[36:37], v[152:153], v[156:157]
	v_pk_fma_f32 v[44:45], v[36:37], v[44:45], v[52:53]
	v_pk_fma_f32 v[154:155], v[38:39], v[154:155], v[158:159]
	v_pk_fma_f32 v[46:47], v[38:39], v[46:47], v[54:55]
	v_pk_add_f32 v[152:153], v[152:153], v[154:155]
	v_pk_add_f32 v[44:45], v[44:45], v[46:47]
	v_add_f32_e32 v142, v152, v153
	v_add_f32_e32 v143, v44, v45
	ds_read_b128 v[76:79], v124 offset:24848
	v_add_f32_dpp v142, v142, v142 quad_perm:[1,0,3,2] row_mask:0xf bank_mask:0xf bound_ctrl:1
	v_add_f32_dpp v143, v143, v143 quad_perm:[1,0,3,2] row_mask:0xf bank_mask:0xf bound_ctrl:1
	ds_read_b128 v[72:75], v124 offset:24832
	v_add_f32_dpp v142, v142, v142 quad_perm:[2,3,0,1] row_mask:0xf bank_mask:0xf bound_ctrl:1
	v_add_f32_dpp v143, v143, v143 quad_perm:[2,3,0,1] row_mask:0xf bank_mask:0xf bound_ctrl:1
	ds_read_b128 v[68:71], v124 offset:25088
	v_add_f32_dpp v142, v142, v142 row_half_mirror row_mask:0xf bank_mask:0xf bound_ctrl:1
	v_add_f32_dpp v143, v143, v143 row_half_mirror row_mask:0xf bank_mask:0xf bound_ctrl:1
	ds_read_b128 v[56:59], v124 offset:25104
	ds_read_b32 v0, v135 offset:25856
	ds_read_b128 v[64:67], v124 offset:25344
	ds_read_b128 v[60:63], v124 offset:25360
	ds_read_b128 v[48:51], v124 offset:24576
	ds_read_b128 v[40:43], v124 offset:24592
	v_pk_mul_f32 v[182:183], v[182:183], v[142:143] op_sel_hi:[1,0]
	v_pk_mul_f32 v[184:185], v[184:185], v[142:143] op_sel_hi:[1,0]
	s_mov_b32 vcc_lo, 0x40404040
	v_pk_mul_f32 v[186:187], v[186:187], v[142:143] op_sel_hi:[1,0]
	v_pk_mul_f32 v[188:189], v[188:189], v[142:143] op_sel_hi:[1,0]
	s_mov_b32 vcc_hi, 0x40404040
	v_pk_fma_f32 v[190:191], v[190:191], v[160:161], v[182:183] op_sel_hi:[1,0,1] neg_lo:[0,0,1] neg_hi:[0,0,1]
	v_pk_fma_f32 v[192:193], v[192:193], v[160:161], v[184:185] op_sel_hi:[1,0,1] neg_lo:[0,0,1] neg_hi:[0,0,1]
	v_cndmask_b32_e32 v133, v133, v143, vcc
	v_pk_fma_f32 v[194:195], v[194:195], v[160:161], v[186:187] op_sel_hi:[1,0,1] neg_lo:[0,0,1] neg_hi:[0,0,1]
	v_pk_fma_f32 v[196:197], v[196:197], v[160:161], v[188:189] op_sel_hi:[1,0,1] neg_lo:[0,0,1] neg_hi:[0,0,1]
	ds_read_b128 v[52:55], v124 offset:25616
	ds_read_b128 v[44:47], v124 offset:25600
	v_pk_fma_f32 v[36:37], v[36:37], v[144:145], v[190:191]
	v_pk_fma_f32 v[38:39], v[38:39], v[146:147], v[192:193]
	v_pk_fma_f32 v[32:33], v[32:33], v[148:149], v[194:195]
	v_pk_fma_f32 v[34:35], v[34:35], v[150:151], v[196:197]
	s_waitcnt lgkmcnt(2)
	v_pk_mul_f32 v[76:77], v[32:33], v[76:77]
	v_pk_mul_f32 v[202:203], v[32:33], v[202:203]
	v_pk_mul_f32 v[78:79], v[34:35], v[78:79]
	v_pk_mul_f32 v[204:205], v[34:35], v[204:205]
	v_pk_fma_f32 v[72:73], v[36:37], v[72:73], v[76:77]
	v_pk_fma_f32 v[198:199], v[36:37], v[198:199], v[202:203]
	v_pk_fma_f32 v[74:75], v[38:39], v[74:75], v[78:79]
	v_pk_fma_f32 v[200:201], v[38:39], v[200:201], v[204:205]
	v_pk_add_f32 v[72:73], v[72:73], v[74:75]
	v_pk_add_f32 v[198:199], v[198:199], v[200:201]
	v_add_f32_e32 v142, v72, v73
	v_add_f32_e32 v143, v198, v199
	ds_read_b128 v[156:159], v124 offset:26384
	v_add_f32_dpp v142, v142, v142 quad_perm:[1,0,3,2] row_mask:0xf bank_mask:0xf bound_ctrl:1
	v_add_f32_dpp v143, v143, v143 quad_perm:[1,0,3,2] row_mask:0xf bank_mask:0xf bound_ctrl:1
	ds_read_b128 v[152:155], v124 offset:26368
	v_add_f32_dpp v142, v142, v142 quad_perm:[2,3,0,1] row_mask:0xf bank_mask:0xf bound_ctrl:1
	v_add_f32_dpp v143, v143, v143 quad_perm:[2,3,0,1] row_mask:0xf bank_mask:0xf bound_ctrl:1
	ds_read_b128 v[182:185], v124 offset:26624
	v_add_f32_dpp v142, v142, v142 row_half_mirror row_mask:0xf bank_mask:0xf bound_ctrl:1
	v_add_f32_dpp v143, v143, v143 row_half_mirror row_mask:0xf bank_mask:0xf bound_ctrl:1
	ds_read_b128 v[186:189], v124 offset:26640
	ds_read_b32 v160, v135 offset:27392
	ds_read_b128 v[190:193], v124 offset:26880
	ds_read_b128 v[194:197], v124 offset:26896
	ds_read_b128 v[144:147], v124 offset:26112
	ds_read_b128 v[148:151], v124 offset:26128
	v_pk_mul_f32 v[68:69], v[68:69], v[142:143] op_sel_hi:[1,0]
	v_pk_mul_f32 v[70:71], v[70:71], v[142:143] op_sel_hi:[1,0]
	s_mov_b32 vcc_lo, 0x80808080
	v_pk_mul_f32 v[56:57], v[56:57], v[142:143] op_sel_hi:[1,0]
	v_pk_mul_f32 v[58:59], v[58:59], v[142:143] op_sel_hi:[1,0]
	s_mov_b32 vcc_hi, 0x80808080
	v_pk_fma_f32 v[64:65], v[64:65], v[0:1], v[68:69] op_sel_hi:[1,0,1] neg_lo:[0,0,1] neg_hi:[0,0,1]
	v_pk_fma_f32 v[66:67], v[66:67], v[0:1], v[70:71] op_sel_hi:[1,0,1] neg_lo:[0,0,1] neg_hi:[0,0,1]
	v_cndmask_b32_e32 v133, v133, v143, vcc
	v_pk_fma_f32 v[60:61], v[60:61], v[0:1], v[56:57] op_sel_hi:[1,0,1] neg_lo:[0,0,1] neg_hi:[0,0,1]
	v_pk_fma_f32 v[62:63], v[62:63], v[0:1], v[58:59] op_sel_hi:[1,0,1] neg_lo:[0,0,1] neg_hi:[0,0,1]
	ds_read_b128 v[202:205], v124 offset:27152
	ds_read_b128 v[198:201], v124 offset:27136
	v_pk_fma_f32 v[36:37], v[36:37], v[48:49], v[64:65]
	v_pk_fma_f32 v[38:39], v[38:39], v[50:51], v[66:67]
	v_pk_fma_f32 v[32:33], v[32:33], v[40:41], v[60:61]
	v_pk_fma_f32 v[34:35], v[34:35], v[42:43], v[62:63]
	s_waitcnt lgkmcnt(2)
	v_pk_mul_f32 v[156:157], v[32:33], v[156:157]
	v_pk_mul_f32 v[52:53], v[32:33], v[52:53]
	v_pk_mul_f32 v[158:159], v[34:35], v[158:159]
	v_pk_mul_f32 v[54:55], v[34:35], v[54:55]
	v_pk_fma_f32 v[152:153], v[36:37], v[152:153], v[156:157]
	v_pk_fma_f32 v[44:45], v[36:37], v[44:45], v[52:53]
	v_pk_fma_f32 v[154:155], v[38:39], v[154:155], v[158:159]
	v_pk_fma_f32 v[46:47], v[38:39], v[46:47], v[54:55]
	v_pk_add_f32 v[152:153], v[152:153], v[154:155]
	v_pk_add_f32 v[44:45], v[44:45], v[46:47]
	v_add_f32_e32 v142, v152, v153
	v_add_f32_e32 v143, v44, v45
	ds_read_b128 v[76:79], v124 offset:27920
	v_add_f32_dpp v142, v142, v142 quad_perm:[1,0,3,2] row_mask:0xf bank_mask:0xf bound_ctrl:1
	v_add_f32_dpp v143, v143, v143 quad_perm:[1,0,3,2] row_mask:0xf bank_mask:0xf bound_ctrl:1
	ds_read_b128 v[72:75], v124 offset:27904
	v_add_f32_dpp v142, v142, v142 quad_perm:[2,3,0,1] row_mask:0xf bank_mask:0xf bound_ctrl:1
	v_add_f32_dpp v143, v143, v143 quad_perm:[2,3,0,1] row_mask:0xf bank_mask:0xf bound_ctrl:1
	ds_read_b128 v[68:71], v124 offset:28160
	v_add_f32_dpp v142, v142, v142 row_half_mirror row_mask:0xf bank_mask:0xf bound_ctrl:1
	v_add_f32_dpp v143, v143, v143 row_half_mirror row_mask:0xf bank_mask:0xf bound_ctrl:1
	ds_read_b128 v[56:59], v124 offset:28176
	ds_read_b32 v0, v135 offset:28928
	ds_read_b128 v[64:67], v124 offset:28416
	ds_read_b128 v[60:63], v124 offset:28432
	ds_read_b128 v[48:51], v124 offset:27648
	ds_read_b128 v[40:43], v124 offset:27664
	v_pk_mul_f32 v[182:183], v[182:183], v[142:143] op_sel_hi:[1,0]
	v_pk_mul_f32 v[184:185], v[184:185], v[142:143] op_sel_hi:[1,0]
	s_mov_b32 vcc_lo, 0x1010101
	v_pk_mul_f32 v[186:187], v[186:187], v[142:143] op_sel_hi:[1,0]
	v_pk_mul_f32 v[188:189], v[188:189], v[142:143] op_sel_hi:[1,0]
	s_mov_b32 vcc_hi, 0x1010101
	v_pk_fma_f32 v[190:191], v[190:191], v[160:161], v[182:183] op_sel_hi:[1,0,1] neg_lo:[0,0,1] neg_hi:[0,0,1]
	v_pk_fma_f32 v[192:193], v[192:193], v[160:161], v[184:185] op_sel_hi:[1,0,1] neg_lo:[0,0,1] neg_hi:[0,0,1]
	v_cndmask_b32_e32 v132, v132, v143, vcc
	v_pk_fma_f32 v[194:195], v[194:195], v[160:161], v[186:187] op_sel_hi:[1,0,1] neg_lo:[0,0,1] neg_hi:[0,0,1]
	v_pk_fma_f32 v[196:197], v[196:197], v[160:161], v[188:189] op_sel_hi:[1,0,1] neg_lo:[0,0,1] neg_hi:[0,0,1]
	ds_read_b128 v[52:55], v124 offset:28688
	ds_read_b128 v[44:47], v124 offset:28672
	v_pk_fma_f32 v[36:37], v[36:37], v[144:145], v[190:191]
	v_pk_fma_f32 v[38:39], v[38:39], v[146:147], v[192:193]
	v_pk_fma_f32 v[32:33], v[32:33], v[148:149], v[194:195]
	v_pk_fma_f32 v[34:35], v[34:35], v[150:151], v[196:197]
	s_waitcnt lgkmcnt(2)
	v_pk_mul_f32 v[76:77], v[32:33], v[76:77]
	v_pk_mul_f32 v[202:203], v[32:33], v[202:203]
	v_pk_mul_f32 v[78:79], v[34:35], v[78:79]
	v_pk_mul_f32 v[204:205], v[34:35], v[204:205]
	v_pk_fma_f32 v[72:73], v[36:37], v[72:73], v[76:77]
	v_pk_fma_f32 v[198:199], v[36:37], v[198:199], v[202:203]
	v_pk_fma_f32 v[74:75], v[38:39], v[74:75], v[78:79]
	v_pk_fma_f32 v[200:201], v[38:39], v[200:201], v[204:205]
	v_pk_add_f32 v[72:73], v[72:73], v[74:75]
	v_pk_add_f32 v[198:199], v[198:199], v[200:201]
	v_add_f32_e32 v142, v72, v73
	v_add_f32_e32 v143, v198, v199
	ds_read_b128 v[156:159], v124 offset:29456
	v_add_f32_dpp v142, v142, v142 quad_perm:[1,0,3,2] row_mask:0xf bank_mask:0xf bound_ctrl:1
	v_add_f32_dpp v143, v143, v143 quad_perm:[1,0,3,2] row_mask:0xf bank_mask:0xf bound_ctrl:1
	ds_read_b128 v[152:155], v124 offset:29440
	v_add_f32_dpp v142, v142, v142 quad_perm:[2,3,0,1] row_mask:0xf bank_mask:0xf bound_ctrl:1
	v_add_f32_dpp v143, v143, v143 quad_perm:[2,3,0,1] row_mask:0xf bank_mask:0xf bound_ctrl:1
	ds_read_b128 v[182:185], v124 offset:29696
	v_add_f32_dpp v142, v142, v142 row_half_mirror row_mask:0xf bank_mask:0xf bound_ctrl:1
	v_add_f32_dpp v143, v143, v143 row_half_mirror row_mask:0xf bank_mask:0xf bound_ctrl:1
	ds_read_b128 v[186:189], v124 offset:29712
	ds_read_b32 v160, v135 offset:30464
	ds_read_b128 v[190:193], v124 offset:29952
	ds_read_b128 v[194:197], v124 offset:29968
	ds_read_b128 v[144:147], v124 offset:29184
	ds_read_b128 v[148:151], v124 offset:29200
	v_pk_mul_f32 v[68:69], v[68:69], v[142:143] op_sel_hi:[1,0]
	v_pk_mul_f32 v[70:71], v[70:71], v[142:143] op_sel_hi:[1,0]
	s_mov_b32 vcc_lo, 0x2020202
	v_pk_mul_f32 v[56:57], v[56:57], v[142:143] op_sel_hi:[1,0]
	v_pk_mul_f32 v[58:59], v[58:59], v[142:143] op_sel_hi:[1,0]
	s_mov_b32 vcc_hi, 0x2020202
	v_pk_fma_f32 v[64:65], v[64:65], v[0:1], v[68:69] op_sel_hi:[1,0,1] neg_lo:[0,0,1] neg_hi:[0,0,1]
	v_pk_fma_f32 v[66:67], v[66:67], v[0:1], v[70:71] op_sel_hi:[1,0,1] neg_lo:[0,0,1] neg_hi:[0,0,1]
	v_cndmask_b32_e32 v132, v132, v143, vcc
	v_pk_fma_f32 v[60:61], v[60:61], v[0:1], v[56:57] op_sel_hi:[1,0,1] neg_lo:[0,0,1] neg_hi:[0,0,1]
	v_pk_fma_f32 v[62:63], v[62:63], v[0:1], v[58:59] op_sel_hi:[1,0,1] neg_lo:[0,0,1] neg_hi:[0,0,1]
	ds_read_b128 v[202:205], v124 offset:30224
	ds_read_b128 v[198:201], v124 offset:30208
	v_pk_fma_f32 v[36:37], v[36:37], v[48:49], v[64:65]
	v_pk_fma_f32 v[38:39], v[38:39], v[50:51], v[66:67]
	v_pk_fma_f32 v[32:33], v[32:33], v[40:41], v[60:61]
	v_pk_fma_f32 v[34:35], v[34:35], v[42:43], v[62:63]
	s_waitcnt lgkmcnt(2)
	v_pk_mul_f32 v[156:157], v[32:33], v[156:157]
	v_pk_mul_f32 v[52:53], v[32:33], v[52:53]
	v_pk_mul_f32 v[158:159], v[34:35], v[158:159]
	v_pk_mul_f32 v[54:55], v[34:35], v[54:55]
	v_pk_fma_f32 v[152:153], v[36:37], v[152:153], v[156:157]
	v_pk_fma_f32 v[44:45], v[36:37], v[44:45], v[52:53]
	v_pk_fma_f32 v[154:155], v[38:39], v[154:155], v[158:159]
	v_pk_fma_f32 v[46:47], v[38:39], v[46:47], v[54:55]
	v_pk_add_f32 v[152:153], v[152:153], v[154:155]
	v_pk_add_f32 v[44:45], v[44:45], v[46:47]
	v_add_f32_e32 v142, v152, v153
	v_add_f32_e32 v143, v44, v45
	ds_read_b128 v[76:79], v124 offset:30992
	v_add_f32_dpp v142, v142, v142 quad_perm:[1,0,3,2] row_mask:0xf bank_mask:0xf bound_ctrl:1
	v_add_f32_dpp v143, v143, v143 quad_perm:[1,0,3,2] row_mask:0xf bank_mask:0xf bound_ctrl:1
	ds_read_b128 v[72:75], v124 offset:30976
	v_add_f32_dpp v142, v142, v142 quad_perm:[2,3,0,1] row_mask:0xf bank_mask:0xf bound_ctrl:1
	v_add_f32_dpp v143, v143, v143 quad_perm:[2,3,0,1] row_mask:0xf bank_mask:0xf bound_ctrl:1
	ds_read_b128 v[68:71], v124 offset:31232
	v_add_f32_dpp v142, v142, v142 row_half_mirror row_mask:0xf bank_mask:0xf bound_ctrl:1
	v_add_f32_dpp v143, v143, v143 row_half_mirror row_mask:0xf bank_mask:0xf bound_ctrl:1
	ds_read_b128 v[56:59], v124 offset:31248
	ds_read_b32 v0, v135 offset:32000
	ds_read_b128 v[64:67], v124 offset:31488
	ds_read_b128 v[60:63], v124 offset:31504
	ds_read_b128 v[48:51], v124 offset:30720
	ds_read_b128 v[40:43], v124 offset:30736
	v_pk_mul_f32 v[182:183], v[182:183], v[142:143] op_sel_hi:[1,0]
	v_pk_mul_f32 v[184:185], v[184:185], v[142:143] op_sel_hi:[1,0]
	s_mov_b32 vcc_lo, 0x4040404
	v_pk_mul_f32 v[186:187], v[186:187], v[142:143] op_sel_hi:[1,0]
	v_pk_mul_f32 v[188:189], v[188:189], v[142:143] op_sel_hi:[1,0]
	s_mov_b32 vcc_hi, 0x4040404
	v_pk_fma_f32 v[190:191], v[190:191], v[160:161], v[182:183] op_sel_hi:[1,0,1] neg_lo:[0,0,1] neg_hi:[0,0,1]
	v_pk_fma_f32 v[192:193], v[192:193], v[160:161], v[184:185] op_sel_hi:[1,0,1] neg_lo:[0,0,1] neg_hi:[0,0,1]
	v_cndmask_b32_e32 v132, v132, v143, vcc
	v_pk_fma_f32 v[194:195], v[194:195], v[160:161], v[186:187] op_sel_hi:[1,0,1] neg_lo:[0,0,1] neg_hi:[0,0,1]
	v_pk_fma_f32 v[196:197], v[196:197], v[160:161], v[188:189] op_sel_hi:[1,0,1] neg_lo:[0,0,1] neg_hi:[0,0,1]
	ds_read_b128 v[52:55], v124 offset:31760
	ds_read_b128 v[44:47], v124 offset:31744
	v_pk_fma_f32 v[36:37], v[36:37], v[144:145], v[190:191]
	v_pk_fma_f32 v[38:39], v[38:39], v[146:147], v[192:193]
	v_pk_fma_f32 v[32:33], v[32:33], v[148:149], v[194:195]
	v_pk_fma_f32 v[34:35], v[34:35], v[150:151], v[196:197]
	s_waitcnt lgkmcnt(2)
	v_pk_mul_f32 v[76:77], v[32:33], v[76:77]
	v_pk_mul_f32 v[202:203], v[32:33], v[202:203]
	v_pk_mul_f32 v[78:79], v[34:35], v[78:79]
	v_pk_mul_f32 v[204:205], v[34:35], v[204:205]
	v_pk_fma_f32 v[72:73], v[36:37], v[72:73], v[76:77]
	v_pk_fma_f32 v[198:199], v[36:37], v[198:199], v[202:203]
	v_pk_fma_f32 v[74:75], v[38:39], v[74:75], v[78:79]
	v_pk_fma_f32 v[200:201], v[38:39], v[200:201], v[204:205]
	v_pk_add_f32 v[72:73], v[72:73], v[74:75]
	v_pk_add_f32 v[198:199], v[198:199], v[200:201]
	v_add_f32_e32 v142, v72, v73
	v_add_f32_e32 v143, v198, v199
	ds_read_b128 v[156:159], v124 offset:32528
	v_add_f32_dpp v142, v142, v142 quad_perm:[1,0,3,2] row_mask:0xf bank_mask:0xf bound_ctrl:1
	v_add_f32_dpp v143, v143, v143 quad_perm:[1,0,3,2] row_mask:0xf bank_mask:0xf bound_ctrl:1
	ds_read_b128 v[152:155], v124 offset:32512
	v_add_f32_dpp v142, v142, v142 quad_perm:[2,3,0,1] row_mask:0xf bank_mask:0xf bound_ctrl:1
	v_add_f32_dpp v143, v143, v143 quad_perm:[2,3,0,1] row_mask:0xf bank_mask:0xf bound_ctrl:1
	ds_read_b128 v[182:185], v124 offset:32768
	v_add_f32_dpp v142, v142, v142 row_half_mirror row_mask:0xf bank_mask:0xf bound_ctrl:1
	v_add_f32_dpp v143, v143, v143 row_half_mirror row_mask:0xf bank_mask:0xf bound_ctrl:1
	ds_read_b128 v[186:189], v124 offset:32784
	ds_read_b32 v160, v135 offset:33536
	ds_read_b128 v[190:193], v124 offset:33024
	ds_read_b128 v[194:197], v124 offset:33040
	ds_read_b128 v[144:147], v124 offset:32256
	ds_read_b128 v[148:151], v124 offset:32272
	v_pk_mul_f32 v[68:69], v[68:69], v[142:143] op_sel_hi:[1,0]
	v_pk_mul_f32 v[70:71], v[70:71], v[142:143] op_sel_hi:[1,0]
	s_mov_b32 vcc_lo, 0x8080808
	v_pk_mul_f32 v[56:57], v[56:57], v[142:143] op_sel_hi:[1,0]
	v_pk_mul_f32 v[58:59], v[58:59], v[142:143] op_sel_hi:[1,0]
	s_mov_b32 vcc_hi, 0x8080808
	v_pk_fma_f32 v[64:65], v[64:65], v[0:1], v[68:69] op_sel_hi:[1,0,1] neg_lo:[0,0,1] neg_hi:[0,0,1]
	v_pk_fma_f32 v[66:67], v[66:67], v[0:1], v[70:71] op_sel_hi:[1,0,1] neg_lo:[0,0,1] neg_hi:[0,0,1]
	v_cndmask_b32_e32 v132, v132, v143, vcc
	v_pk_fma_f32 v[60:61], v[60:61], v[0:1], v[56:57] op_sel_hi:[1,0,1] neg_lo:[0,0,1] neg_hi:[0,0,1]
	v_pk_fma_f32 v[62:63], v[62:63], v[0:1], v[58:59] op_sel_hi:[1,0,1] neg_lo:[0,0,1] neg_hi:[0,0,1]
	ds_read_b128 v[202:205], v124 offset:33296
	ds_read_b128 v[198:201], v124 offset:33280
	v_pk_fma_f32 v[36:37], v[36:37], v[48:49], v[64:65]
	v_pk_fma_f32 v[38:39], v[38:39], v[50:51], v[66:67]
	v_pk_fma_f32 v[32:33], v[32:33], v[40:41], v[60:61]
	v_pk_fma_f32 v[34:35], v[34:35], v[42:43], v[62:63]
	s_waitcnt lgkmcnt(2)
	v_pk_mul_f32 v[156:157], v[32:33], v[156:157]
	v_pk_mul_f32 v[52:53], v[32:33], v[52:53]
	v_pk_mul_f32 v[158:159], v[34:35], v[158:159]
	v_pk_mul_f32 v[54:55], v[34:35], v[54:55]
	v_pk_fma_f32 v[152:153], v[36:37], v[152:153], v[156:157]
	v_pk_fma_f32 v[44:45], v[36:37], v[44:45], v[52:53]
	v_pk_fma_f32 v[154:155], v[38:39], v[154:155], v[158:159]
	v_pk_fma_f32 v[46:47], v[38:39], v[46:47], v[54:55]
	v_pk_add_f32 v[152:153], v[152:153], v[154:155]
	v_pk_add_f32 v[44:45], v[44:45], v[46:47]
	v_add_f32_e32 v142, v152, v153
	v_add_f32_e32 v143, v44, v45
	ds_read_b128 v[76:79], v124 offset:34064
	v_add_f32_dpp v142, v142, v142 quad_perm:[1,0,3,2] row_mask:0xf bank_mask:0xf bound_ctrl:1
	v_add_f32_dpp v143, v143, v143 quad_perm:[1,0,3,2] row_mask:0xf bank_mask:0xf bound_ctrl:1
	ds_read_b128 v[72:75], v124 offset:34048
	v_add_f32_dpp v142, v142, v142 quad_perm:[2,3,0,1] row_mask:0xf bank_mask:0xf bound_ctrl:1
	v_add_f32_dpp v143, v143, v143 quad_perm:[2,3,0,1] row_mask:0xf bank_mask:0xf bound_ctrl:1
	ds_read_b128 v[68:71], v124 offset:34304
	v_add_f32_dpp v142, v142, v142 row_half_mirror row_mask:0xf bank_mask:0xf bound_ctrl:1
	v_add_f32_dpp v143, v143, v143 row_half_mirror row_mask:0xf bank_mask:0xf bound_ctrl:1
	ds_read_b128 v[56:59], v124 offset:34320
	ds_read_b32 v0, v135 offset:35072
	ds_read_b128 v[64:67], v124 offset:34560
	ds_read_b128 v[60:63], v124 offset:34576
	ds_read_b128 v[48:51], v124 offset:33792
	ds_read_b128 v[40:43], v124 offset:33808
	v_pk_mul_f32 v[182:183], v[182:183], v[142:143] op_sel_hi:[1,0]
	v_pk_mul_f32 v[184:185], v[184:185], v[142:143] op_sel_hi:[1,0]
	s_mov_b32 vcc_lo, 0x10101010
	v_pk_mul_f32 v[186:187], v[186:187], v[142:143] op_sel_hi:[1,0]
	v_pk_mul_f32 v[188:189], v[188:189], v[142:143] op_sel_hi:[1,0]
	s_mov_b32 vcc_hi, 0x10101010
	v_pk_fma_f32 v[190:191], v[190:191], v[160:161], v[182:183] op_sel_hi:[1,0,1] neg_lo:[0,0,1] neg_hi:[0,0,1]
	v_pk_fma_f32 v[192:193], v[192:193], v[160:161], v[184:185] op_sel_hi:[1,0,1] neg_lo:[0,0,1] neg_hi:[0,0,1]
	v_cndmask_b32_e32 v132, v132, v143, vcc
	v_pk_fma_f32 v[194:195], v[194:195], v[160:161], v[186:187] op_sel_hi:[1,0,1] neg_lo:[0,0,1] neg_hi:[0,0,1]
	v_pk_fma_f32 v[196:197], v[196:197], v[160:161], v[188:189] op_sel_hi:[1,0,1] neg_lo:[0,0,1] neg_hi:[0,0,1]
	ds_read_b128 v[52:55], v124 offset:34832
	ds_read_b128 v[44:47], v124 offset:34816
	v_pk_fma_f32 v[36:37], v[36:37], v[144:145], v[190:191]
	v_pk_fma_f32 v[38:39], v[38:39], v[146:147], v[192:193]
	v_pk_fma_f32 v[32:33], v[32:33], v[148:149], v[194:195]
	v_pk_fma_f32 v[34:35], v[34:35], v[150:151], v[196:197]
	s_waitcnt lgkmcnt(2)
	v_pk_mul_f32 v[76:77], v[32:33], v[76:77]
	v_pk_mul_f32 v[202:203], v[32:33], v[202:203]
	v_pk_mul_f32 v[78:79], v[34:35], v[78:79]
	v_pk_mul_f32 v[204:205], v[34:35], v[204:205]
	v_pk_fma_f32 v[72:73], v[36:37], v[72:73], v[76:77]
	v_pk_fma_f32 v[198:199], v[36:37], v[198:199], v[202:203]
	v_pk_fma_f32 v[74:75], v[38:39], v[74:75], v[78:79]
	v_pk_fma_f32 v[200:201], v[38:39], v[200:201], v[204:205]
	v_pk_add_f32 v[72:73], v[72:73], v[74:75]
	v_pk_add_f32 v[198:199], v[198:199], v[200:201]
	v_add_f32_e32 v142, v72, v73
	v_add_f32_e32 v143, v198, v199
	ds_read_b128 v[156:159], v124 offset:35600
	v_add_f32_dpp v142, v142, v142 quad_perm:[1,0,3,2] row_mask:0xf bank_mask:0xf bound_ctrl:1
	v_add_f32_dpp v143, v143, v143 quad_perm:[1,0,3,2] row_mask:0xf bank_mask:0xf bound_ctrl:1
	ds_read_b128 v[152:155], v124 offset:35584
	v_add_f32_dpp v142, v142, v142 quad_perm:[2,3,0,1] row_mask:0xf bank_mask:0xf bound_ctrl:1
	v_add_f32_dpp v143, v143, v143 quad_perm:[2,3,0,1] row_mask:0xf bank_mask:0xf bound_ctrl:1
	ds_read_b128 v[182:185], v124 offset:35840
	v_add_f32_dpp v142, v142, v142 row_half_mirror row_mask:0xf bank_mask:0xf bound_ctrl:1
	v_add_f32_dpp v143, v143, v143 row_half_mirror row_mask:0xf bank_mask:0xf bound_ctrl:1
	ds_read_b128 v[186:189], v124 offset:35856
	ds_read_b32 v160, v135 offset:36608
	ds_read_b128 v[190:193], v124 offset:36096
	ds_read_b128 v[194:197], v124 offset:36112
	ds_read_b128 v[144:147], v124 offset:35328
	ds_read_b128 v[148:151], v124 offset:35344
	v_pk_mul_f32 v[68:69], v[68:69], v[142:143] op_sel_hi:[1,0]
	v_pk_mul_f32 v[70:71], v[70:71], v[142:143] op_sel_hi:[1,0]
	s_mov_b32 vcc_lo, 0x20202020
	v_pk_mul_f32 v[56:57], v[56:57], v[142:143] op_sel_hi:[1,0]
	v_pk_mul_f32 v[58:59], v[58:59], v[142:143] op_sel_hi:[1,0]
	s_mov_b32 vcc_hi, 0x20202020
	v_pk_fma_f32 v[64:65], v[64:65], v[0:1], v[68:69] op_sel_hi:[1,0,1] neg_lo:[0,0,1] neg_hi:[0,0,1]
	v_pk_fma_f32 v[66:67], v[66:67], v[0:1], v[70:71] op_sel_hi:[1,0,1] neg_lo:[0,0,1] neg_hi:[0,0,1]
	v_cndmask_b32_e32 v132, v132, v143, vcc
	v_pk_fma_f32 v[60:61], v[60:61], v[0:1], v[56:57] op_sel_hi:[1,0,1] neg_lo:[0,0,1] neg_hi:[0,0,1]
	v_pk_fma_f32 v[62:63], v[62:63], v[0:1], v[58:59] op_sel_hi:[1,0,1] neg_lo:[0,0,1] neg_hi:[0,0,1]
	ds_read_b128 v[202:205], v124 offset:36368
	ds_read_b128 v[198:201], v124 offset:36352
	v_pk_fma_f32 v[36:37], v[36:37], v[48:49], v[64:65]
	v_pk_fma_f32 v[38:39], v[38:39], v[50:51], v[66:67]
	v_pk_fma_f32 v[32:33], v[32:33], v[40:41], v[60:61]
	v_pk_fma_f32 v[34:35], v[34:35], v[42:43], v[62:63]
	s_waitcnt lgkmcnt(2)
	v_pk_mul_f32 v[156:157], v[32:33], v[156:157]
	v_pk_mul_f32 v[52:53], v[32:33], v[52:53]
	v_pk_mul_f32 v[158:159], v[34:35], v[158:159]
	v_pk_mul_f32 v[54:55], v[34:35], v[54:55]
	v_pk_fma_f32 v[152:153], v[36:37], v[152:153], v[156:157]
	v_pk_fma_f32 v[44:45], v[36:37], v[44:45], v[52:53]
	v_pk_fma_f32 v[154:155], v[38:39], v[154:155], v[158:159]
	v_pk_fma_f32 v[46:47], v[38:39], v[46:47], v[54:55]
	v_pk_add_f32 v[152:153], v[152:153], v[154:155]
	v_pk_add_f32 v[44:45], v[44:45], v[46:47]
	v_add_f32_e32 v142, v152, v153
	v_add_f32_e32 v143, v44, v45
	ds_read_b128 v[76:79], v124 offset:37136
	v_add_f32_dpp v142, v142, v142 quad_perm:[1,0,3,2] row_mask:0xf bank_mask:0xf bound_ctrl:1
	v_add_f32_dpp v143, v143, v143 quad_perm:[1,0,3,2] row_mask:0xf bank_mask:0xf bound_ctrl:1
	ds_read_b128 v[72:75], v124 offset:37120
	v_add_f32_dpp v142, v142, v142 quad_perm:[2,3,0,1] row_mask:0xf bank_mask:0xf bound_ctrl:1
	v_add_f32_dpp v143, v143, v143 quad_perm:[2,3,0,1] row_mask:0xf bank_mask:0xf bound_ctrl:1
	ds_read_b128 v[68:71], v124 offset:37376
	v_add_f32_dpp v142, v142, v142 row_half_mirror row_mask:0xf bank_mask:0xf bound_ctrl:1
	v_add_f32_dpp v143, v143, v143 row_half_mirror row_mask:0xf bank_mask:0xf bound_ctrl:1
	ds_read_b128 v[56:59], v124 offset:37392
	ds_read_b32 v0, v135 offset:38144
	ds_read_b128 v[64:67], v124 offset:37632
	ds_read_b128 v[60:63], v124 offset:37648
	ds_read_b128 v[48:51], v124 offset:36864
	ds_read_b128 v[40:43], v124 offset:36880
	v_pk_mul_f32 v[182:183], v[182:183], v[142:143] op_sel_hi:[1,0]
	v_pk_mul_f32 v[184:185], v[184:185], v[142:143] op_sel_hi:[1,0]
	s_mov_b32 vcc_lo, 0x40404040
	v_pk_mul_f32 v[186:187], v[186:187], v[142:143] op_sel_hi:[1,0]
	v_pk_mul_f32 v[188:189], v[188:189], v[142:143] op_sel_hi:[1,0]
	s_mov_b32 vcc_hi, 0x40404040
	v_pk_fma_f32 v[190:191], v[190:191], v[160:161], v[182:183] op_sel_hi:[1,0,1] neg_lo:[0,0,1] neg_hi:[0,0,1]
	v_pk_fma_f32 v[192:193], v[192:193], v[160:161], v[184:185] op_sel_hi:[1,0,1] neg_lo:[0,0,1] neg_hi:[0,0,1]
	v_cndmask_b32_e32 v132, v132, v143, vcc
	v_pk_fma_f32 v[194:195], v[194:195], v[160:161], v[186:187] op_sel_hi:[1,0,1] neg_lo:[0,0,1] neg_hi:[0,0,1]
	v_pk_fma_f32 v[196:197], v[196:197], v[160:161], v[188:189] op_sel_hi:[1,0,1] neg_lo:[0,0,1] neg_hi:[0,0,1]
	ds_read_b128 v[52:55], v124 offset:37904
	ds_read_b128 v[44:47], v124 offset:37888
	v_pk_fma_f32 v[36:37], v[36:37], v[144:145], v[190:191]
	v_pk_fma_f32 v[38:39], v[38:39], v[146:147], v[192:193]
	v_pk_fma_f32 v[32:33], v[32:33], v[148:149], v[194:195]
	v_pk_fma_f32 v[34:35], v[34:35], v[150:151], v[196:197]
	s_waitcnt lgkmcnt(2)
	v_pk_mul_f32 v[76:77], v[32:33], v[76:77]
	v_pk_mul_f32 v[202:203], v[32:33], v[202:203]
	v_pk_mul_f32 v[78:79], v[34:35], v[78:79]
	v_pk_mul_f32 v[204:205], v[34:35], v[204:205]
	v_pk_fma_f32 v[72:73], v[36:37], v[72:73], v[76:77]
	v_pk_fma_f32 v[198:199], v[36:37], v[198:199], v[202:203]
	v_pk_fma_f32 v[74:75], v[38:39], v[74:75], v[78:79]
	v_pk_fma_f32 v[200:201], v[38:39], v[200:201], v[204:205]
	v_pk_add_f32 v[72:73], v[72:73], v[74:75]
	v_pk_add_f32 v[198:199], v[198:199], v[200:201]
	v_add_f32_e32 v142, v72, v73
	v_add_f32_e32 v143, v198, v199
	ds_read_b128 v[156:159], v124 offset:38672
	v_add_f32_dpp v142, v142, v142 quad_perm:[1,0,3,2] row_mask:0xf bank_mask:0xf bound_ctrl:1
	v_add_f32_dpp v143, v143, v143 quad_perm:[1,0,3,2] row_mask:0xf bank_mask:0xf bound_ctrl:1
	ds_read_b128 v[152:155], v124 offset:38656
	v_add_f32_dpp v142, v142, v142 quad_perm:[2,3,0,1] row_mask:0xf bank_mask:0xf bound_ctrl:1
	v_add_f32_dpp v143, v143, v143 quad_perm:[2,3,0,1] row_mask:0xf bank_mask:0xf bound_ctrl:1
	ds_read_b128 v[182:185], v124 offset:38912
	v_add_f32_dpp v142, v142, v142 row_half_mirror row_mask:0xf bank_mask:0xf bound_ctrl:1
	v_add_f32_dpp v143, v143, v143 row_half_mirror row_mask:0xf bank_mask:0xf bound_ctrl:1
	ds_read_b128 v[186:189], v124 offset:38928
	ds_read_b32 v160, v135 offset:39680
	ds_read_b128 v[190:193], v124 offset:39168
	ds_read_b128 v[194:197], v124 offset:39184
	ds_read_b128 v[144:147], v124 offset:38400
	ds_read_b128 v[148:151], v124 offset:38416
	v_pk_mul_f32 v[68:69], v[68:69], v[142:143] op_sel_hi:[1,0]
	v_pk_mul_f32 v[70:71], v[70:71], v[142:143] op_sel_hi:[1,0]
	s_mov_b32 vcc_lo, 0x80808080
	v_pk_mul_f32 v[56:57], v[56:57], v[142:143] op_sel_hi:[1,0]
	v_pk_mul_f32 v[58:59], v[58:59], v[142:143] op_sel_hi:[1,0]
	s_mov_b32 vcc_hi, 0x80808080
	v_pk_fma_f32 v[64:65], v[64:65], v[0:1], v[68:69] op_sel_hi:[1,0,1] neg_lo:[0,0,1] neg_hi:[0,0,1]
	v_pk_fma_f32 v[66:67], v[66:67], v[0:1], v[70:71] op_sel_hi:[1,0,1] neg_lo:[0,0,1] neg_hi:[0,0,1]
	v_cndmask_b32_e32 v132, v132, v143, vcc
	v_pk_fma_f32 v[60:61], v[60:61], v[0:1], v[56:57] op_sel_hi:[1,0,1] neg_lo:[0,0,1] neg_hi:[0,0,1]
	v_pk_fma_f32 v[62:63], v[62:63], v[0:1], v[58:59] op_sel_hi:[1,0,1] neg_lo:[0,0,1] neg_hi:[0,0,1]
	ds_read_b128 v[202:205], v124 offset:39440
	ds_read_b128 v[198:201], v124 offset:39424
	v_pk_fma_f32 v[36:37], v[36:37], v[48:49], v[64:65]
	v_pk_fma_f32 v[38:39], v[38:39], v[50:51], v[66:67]
	v_pk_fma_f32 v[32:33], v[32:33], v[40:41], v[60:61]
	v_pk_fma_f32 v[34:35], v[34:35], v[42:43], v[62:63]
	s_waitcnt lgkmcnt(2)
	v_pk_mul_f32 v[156:157], v[32:33], v[156:157]
	v_pk_mul_f32 v[52:53], v[32:33], v[52:53]
	v_pk_mul_f32 v[158:159], v[34:35], v[158:159]
	v_pk_mul_f32 v[54:55], v[34:35], v[54:55]
	v_pk_fma_f32 v[152:153], v[36:37], v[152:153], v[156:157]
	v_pk_fma_f32 v[44:45], v[36:37], v[44:45], v[52:53]
	v_pk_fma_f32 v[154:155], v[38:39], v[154:155], v[158:159]
	v_pk_fma_f32 v[46:47], v[38:39], v[46:47], v[54:55]
	v_pk_add_f32 v[152:153], v[152:153], v[154:155]
	v_pk_add_f32 v[44:45], v[44:45], v[46:47]
	v_add_f32_e32 v142, v152, v153
	v_add_f32_e32 v143, v44, v45
	ds_read_b128 v[76:79], v124 offset:40208
	v_add_f32_dpp v142, v142, v142 quad_perm:[1,0,3,2] row_mask:0xf bank_mask:0xf bound_ctrl:1
	v_add_f32_dpp v143, v143, v143 quad_perm:[1,0,3,2] row_mask:0xf bank_mask:0xf bound_ctrl:1
	ds_read_b128 v[72:75], v124 offset:40192
	v_add_f32_dpp v142, v142, v142 quad_perm:[2,3,0,1] row_mask:0xf bank_mask:0xf bound_ctrl:1
	v_add_f32_dpp v143, v143, v143 quad_perm:[2,3,0,1] row_mask:0xf bank_mask:0xf bound_ctrl:1
	ds_read_b128 v[68:71], v124 offset:40448
	v_add_f32_dpp v142, v142, v142 row_half_mirror row_mask:0xf bank_mask:0xf bound_ctrl:1
	v_add_f32_dpp v143, v143, v143 row_half_mirror row_mask:0xf bank_mask:0xf bound_ctrl:1
	ds_read_b128 v[56:59], v124 offset:40464
	ds_read_b32 v0, v135 offset:41216
	ds_read_b128 v[64:67], v124 offset:40704
	ds_read_b128 v[60:63], v124 offset:40720
	ds_read_b128 v[48:51], v124 offset:39936
	ds_read_b128 v[40:43], v124 offset:39952
	v_pk_mul_f32 v[182:183], v[182:183], v[142:143] op_sel_hi:[1,0]
	v_pk_mul_f32 v[184:185], v[184:185], v[142:143] op_sel_hi:[1,0]
	s_mov_b32 vcc_lo, 0x1010101
	v_pk_mul_f32 v[186:187], v[186:187], v[142:143] op_sel_hi:[1,0]
	v_pk_mul_f32 v[188:189], v[188:189], v[142:143] op_sel_hi:[1,0]
	s_mov_b32 vcc_hi, 0x1010101
	v_pk_fma_f32 v[190:191], v[190:191], v[160:161], v[182:183] op_sel_hi:[1,0,1] neg_lo:[0,0,1] neg_hi:[0,0,1]
	v_pk_fma_f32 v[192:193], v[192:193], v[160:161], v[184:185] op_sel_hi:[1,0,1] neg_lo:[0,0,1] neg_hi:[0,0,1]
	v_cndmask_b32_e32 v131, v131, v143, vcc
	v_pk_fma_f32 v[194:195], v[194:195], v[160:161], v[186:187] op_sel_hi:[1,0,1] neg_lo:[0,0,1] neg_hi:[0,0,1]
	v_pk_fma_f32 v[196:197], v[196:197], v[160:161], v[188:189] op_sel_hi:[1,0,1] neg_lo:[0,0,1] neg_hi:[0,0,1]
	ds_read_b128 v[52:55], v124 offset:40976
	ds_read_b128 v[44:47], v124 offset:40960
	v_pk_fma_f32 v[36:37], v[36:37], v[144:145], v[190:191]
	v_pk_fma_f32 v[38:39], v[38:39], v[146:147], v[192:193]
	v_pk_fma_f32 v[32:33], v[32:33], v[148:149], v[194:195]
	v_pk_fma_f32 v[34:35], v[34:35], v[150:151], v[196:197]
	s_waitcnt lgkmcnt(2)
	v_pk_mul_f32 v[76:77], v[32:33], v[76:77]
	v_pk_mul_f32 v[202:203], v[32:33], v[202:203]
	v_pk_mul_f32 v[78:79], v[34:35], v[78:79]
	v_pk_mul_f32 v[204:205], v[34:35], v[204:205]
	v_pk_fma_f32 v[72:73], v[36:37], v[72:73], v[76:77]
	v_pk_fma_f32 v[198:199], v[36:37], v[198:199], v[202:203]
	v_pk_fma_f32 v[74:75], v[38:39], v[74:75], v[78:79]
	v_pk_fma_f32 v[200:201], v[38:39], v[200:201], v[204:205]
	v_pk_add_f32 v[72:73], v[72:73], v[74:75]
	v_pk_add_f32 v[198:199], v[198:199], v[200:201]
	v_add_f32_e32 v142, v72, v73
	v_add_f32_e32 v143, v198, v199
	ds_read_b128 v[156:159], v124 offset:41744
	v_add_f32_dpp v142, v142, v142 quad_perm:[1,0,3,2] row_mask:0xf bank_mask:0xf bound_ctrl:1
	v_add_f32_dpp v143, v143, v143 quad_perm:[1,0,3,2] row_mask:0xf bank_mask:0xf bound_ctrl:1
	ds_read_b128 v[152:155], v124 offset:41728
	v_add_f32_dpp v142, v142, v142 quad_perm:[2,3,0,1] row_mask:0xf bank_mask:0xf bound_ctrl:1
	v_add_f32_dpp v143, v143, v143 quad_perm:[2,3,0,1] row_mask:0xf bank_mask:0xf bound_ctrl:1
	ds_read_b128 v[182:185], v124 offset:41984
	v_add_f32_dpp v142, v142, v142 row_half_mirror row_mask:0xf bank_mask:0xf bound_ctrl:1
	v_add_f32_dpp v143, v143, v143 row_half_mirror row_mask:0xf bank_mask:0xf bound_ctrl:1
	ds_read_b128 v[186:189], v124 offset:42000
	ds_read_b32 v160, v135 offset:42752
	ds_read_b128 v[190:193], v124 offset:42240
	ds_read_b128 v[194:197], v124 offset:42256
	ds_read_b128 v[144:147], v124 offset:41472
	ds_read_b128 v[148:151], v124 offset:41488
	v_pk_mul_f32 v[68:69], v[68:69], v[142:143] op_sel_hi:[1,0]
	v_pk_mul_f32 v[70:71], v[70:71], v[142:143] op_sel_hi:[1,0]
	s_mov_b32 vcc_lo, 0x2020202
	v_pk_mul_f32 v[56:57], v[56:57], v[142:143] op_sel_hi:[1,0]
	v_pk_mul_f32 v[58:59], v[58:59], v[142:143] op_sel_hi:[1,0]
	s_mov_b32 vcc_hi, 0x2020202
	v_pk_fma_f32 v[64:65], v[64:65], v[0:1], v[68:69] op_sel_hi:[1,0,1] neg_lo:[0,0,1] neg_hi:[0,0,1]
	v_pk_fma_f32 v[66:67], v[66:67], v[0:1], v[70:71] op_sel_hi:[1,0,1] neg_lo:[0,0,1] neg_hi:[0,0,1]
	v_cndmask_b32_e32 v131, v131, v143, vcc
	v_pk_fma_f32 v[60:61], v[60:61], v[0:1], v[56:57] op_sel_hi:[1,0,1] neg_lo:[0,0,1] neg_hi:[0,0,1]
	v_pk_fma_f32 v[62:63], v[62:63], v[0:1], v[58:59] op_sel_hi:[1,0,1] neg_lo:[0,0,1] neg_hi:[0,0,1]
	ds_read_b128 v[202:205], v124 offset:42512
	ds_read_b128 v[198:201], v124 offset:42496
	v_pk_fma_f32 v[36:37], v[36:37], v[48:49], v[64:65]
	v_pk_fma_f32 v[38:39], v[38:39], v[50:51], v[66:67]
	v_pk_fma_f32 v[32:33], v[32:33], v[40:41], v[60:61]
	v_pk_fma_f32 v[34:35], v[34:35], v[42:43], v[62:63]
	s_waitcnt lgkmcnt(2)
	v_pk_mul_f32 v[156:157], v[32:33], v[156:157]
	v_pk_mul_f32 v[52:53], v[32:33], v[52:53]
	v_pk_mul_f32 v[158:159], v[34:35], v[158:159]
	v_pk_mul_f32 v[54:55], v[34:35], v[54:55]
	v_pk_fma_f32 v[152:153], v[36:37], v[152:153], v[156:157]
	v_pk_fma_f32 v[44:45], v[36:37], v[44:45], v[52:53]
	v_pk_fma_f32 v[154:155], v[38:39], v[154:155], v[158:159]
	v_pk_fma_f32 v[46:47], v[38:39], v[46:47], v[54:55]
	v_pk_add_f32 v[152:153], v[152:153], v[154:155]
	v_pk_add_f32 v[44:45], v[44:45], v[46:47]
	v_add_f32_e32 v142, v152, v153
	v_add_f32_e32 v143, v44, v45
	ds_read_b128 v[76:79], v124 offset:43280
	v_add_f32_dpp v142, v142, v142 quad_perm:[1,0,3,2] row_mask:0xf bank_mask:0xf bound_ctrl:1
	v_add_f32_dpp v143, v143, v143 quad_perm:[1,0,3,2] row_mask:0xf bank_mask:0xf bound_ctrl:1
	ds_read_b128 v[72:75], v124 offset:43264
	v_add_f32_dpp v142, v142, v142 quad_perm:[2,3,0,1] row_mask:0xf bank_mask:0xf bound_ctrl:1
	v_add_f32_dpp v143, v143, v143 quad_perm:[2,3,0,1] row_mask:0xf bank_mask:0xf bound_ctrl:1
	ds_read_b128 v[68:71], v124 offset:43520
	v_add_f32_dpp v142, v142, v142 row_half_mirror row_mask:0xf bank_mask:0xf bound_ctrl:1
	v_add_f32_dpp v143, v143, v143 row_half_mirror row_mask:0xf bank_mask:0xf bound_ctrl:1
	ds_read_b128 v[56:59], v124 offset:43536
	ds_read_b32 v0, v135 offset:44288
	ds_read_b128 v[64:67], v124 offset:43776
	ds_read_b128 v[60:63], v124 offset:43792
	ds_read_b128 v[48:51], v124 offset:43008
	ds_read_b128 v[40:43], v124 offset:43024
	v_pk_mul_f32 v[182:183], v[182:183], v[142:143] op_sel_hi:[1,0]
	v_pk_mul_f32 v[184:185], v[184:185], v[142:143] op_sel_hi:[1,0]
	s_mov_b32 vcc_lo, 0x4040404
	v_pk_mul_f32 v[186:187], v[186:187], v[142:143] op_sel_hi:[1,0]
	v_pk_mul_f32 v[188:189], v[188:189], v[142:143] op_sel_hi:[1,0]
	s_mov_b32 vcc_hi, 0x4040404
	v_pk_fma_f32 v[190:191], v[190:191], v[160:161], v[182:183] op_sel_hi:[1,0,1] neg_lo:[0,0,1] neg_hi:[0,0,1]
	v_pk_fma_f32 v[192:193], v[192:193], v[160:161], v[184:185] op_sel_hi:[1,0,1] neg_lo:[0,0,1] neg_hi:[0,0,1]
	v_cndmask_b32_e32 v131, v131, v143, vcc
	v_pk_fma_f32 v[194:195], v[194:195], v[160:161], v[186:187] op_sel_hi:[1,0,1] neg_lo:[0,0,1] neg_hi:[0,0,1]
	v_pk_fma_f32 v[196:197], v[196:197], v[160:161], v[188:189] op_sel_hi:[1,0,1] neg_lo:[0,0,1] neg_hi:[0,0,1]
	ds_read_b128 v[52:55], v124 offset:44048
	ds_read_b128 v[44:47], v124 offset:44032
	v_pk_fma_f32 v[36:37], v[36:37], v[144:145], v[190:191]
	v_pk_fma_f32 v[38:39], v[38:39], v[146:147], v[192:193]
	v_pk_fma_f32 v[32:33], v[32:33], v[148:149], v[194:195]
	v_pk_fma_f32 v[34:35], v[34:35], v[150:151], v[196:197]
	s_waitcnt lgkmcnt(2)
	v_pk_mul_f32 v[76:77], v[32:33], v[76:77]
	v_pk_mul_f32 v[202:203], v[32:33], v[202:203]
	v_pk_mul_f32 v[78:79], v[34:35], v[78:79]
	v_pk_mul_f32 v[204:205], v[34:35], v[204:205]
	v_pk_fma_f32 v[72:73], v[36:37], v[72:73], v[76:77]
	v_pk_fma_f32 v[198:199], v[36:37], v[198:199], v[202:203]
	v_pk_fma_f32 v[74:75], v[38:39], v[74:75], v[78:79]
	v_pk_fma_f32 v[200:201], v[38:39], v[200:201], v[204:205]
	v_pk_add_f32 v[72:73], v[72:73], v[74:75]
	v_pk_add_f32 v[198:199], v[198:199], v[200:201]
	v_add_f32_e32 v142, v72, v73
	v_add_f32_e32 v143, v198, v199
	ds_read_b128 v[156:159], v124 offset:44816
	v_add_f32_dpp v142, v142, v142 quad_perm:[1,0,3,2] row_mask:0xf bank_mask:0xf bound_ctrl:1
	v_add_f32_dpp v143, v143, v143 quad_perm:[1,0,3,2] row_mask:0xf bank_mask:0xf bound_ctrl:1
	ds_read_b128 v[152:155], v124 offset:44800
	v_add_f32_dpp v142, v142, v142 quad_perm:[2,3,0,1] row_mask:0xf bank_mask:0xf bound_ctrl:1
	v_add_f32_dpp v143, v143, v143 quad_perm:[2,3,0,1] row_mask:0xf bank_mask:0xf bound_ctrl:1
	ds_read_b128 v[182:185], v124 offset:45056
	v_add_f32_dpp v142, v142, v142 row_half_mirror row_mask:0xf bank_mask:0xf bound_ctrl:1
	v_add_f32_dpp v143, v143, v143 row_half_mirror row_mask:0xf bank_mask:0xf bound_ctrl:1
	ds_read_b128 v[186:189], v124 offset:45072
	ds_read_b32 v160, v135 offset:45824
	ds_read_b128 v[190:193], v124 offset:45312
	ds_read_b128 v[194:197], v124 offset:45328
	ds_read_b128 v[144:147], v124 offset:44544
	ds_read_b128 v[148:151], v124 offset:44560
	v_pk_mul_f32 v[68:69], v[68:69], v[142:143] op_sel_hi:[1,0]
	v_pk_mul_f32 v[70:71], v[70:71], v[142:143] op_sel_hi:[1,0]
	s_mov_b32 vcc_lo, 0x8080808
	v_pk_mul_f32 v[56:57], v[56:57], v[142:143] op_sel_hi:[1,0]
	v_pk_mul_f32 v[58:59], v[58:59], v[142:143] op_sel_hi:[1,0]
	s_mov_b32 vcc_hi, 0x8080808
	v_pk_fma_f32 v[64:65], v[64:65], v[0:1], v[68:69] op_sel_hi:[1,0,1] neg_lo:[0,0,1] neg_hi:[0,0,1]
	v_pk_fma_f32 v[66:67], v[66:67], v[0:1], v[70:71] op_sel_hi:[1,0,1] neg_lo:[0,0,1] neg_hi:[0,0,1]
	v_cndmask_b32_e32 v131, v131, v143, vcc
	v_pk_fma_f32 v[60:61], v[60:61], v[0:1], v[56:57] op_sel_hi:[1,0,1] neg_lo:[0,0,1] neg_hi:[0,0,1]
	v_pk_fma_f32 v[62:63], v[62:63], v[0:1], v[58:59] op_sel_hi:[1,0,1] neg_lo:[0,0,1] neg_hi:[0,0,1]
	ds_read_b128 v[202:205], v124 offset:45584
	ds_read_b128 v[198:201], v124 offset:45568
	v_pk_fma_f32 v[36:37], v[36:37], v[48:49], v[64:65]
	v_pk_fma_f32 v[38:39], v[38:39], v[50:51], v[66:67]
	v_pk_fma_f32 v[32:33], v[32:33], v[40:41], v[60:61]
	v_pk_fma_f32 v[34:35], v[34:35], v[42:43], v[62:63]
	s_waitcnt lgkmcnt(2)
	v_pk_mul_f32 v[156:157], v[32:33], v[156:157]
	v_pk_mul_f32 v[52:53], v[32:33], v[52:53]
	v_pk_mul_f32 v[158:159], v[34:35], v[158:159]
	v_pk_mul_f32 v[54:55], v[34:35], v[54:55]
	v_pk_fma_f32 v[152:153], v[36:37], v[152:153], v[156:157]
	v_pk_fma_f32 v[44:45], v[36:37], v[44:45], v[52:53]
	v_pk_fma_f32 v[154:155], v[38:39], v[154:155], v[158:159]
	v_pk_fma_f32 v[46:47], v[38:39], v[46:47], v[54:55]
	v_pk_add_f32 v[152:153], v[152:153], v[154:155]
	v_pk_add_f32 v[44:45], v[44:45], v[46:47]
	v_add_f32_e32 v142, v152, v153
	v_add_f32_e32 v143, v44, v45
	ds_read_b128 v[76:79], v124 offset:46352
	v_add_f32_dpp v142, v142, v142 quad_perm:[1,0,3,2] row_mask:0xf bank_mask:0xf bound_ctrl:1
	v_add_f32_dpp v143, v143, v143 quad_perm:[1,0,3,2] row_mask:0xf bank_mask:0xf bound_ctrl:1
	ds_read_b128 v[72:75], v124 offset:46336
	v_add_f32_dpp v142, v142, v142 quad_perm:[2,3,0,1] row_mask:0xf bank_mask:0xf bound_ctrl:1
	v_add_f32_dpp v143, v143, v143 quad_perm:[2,3,0,1] row_mask:0xf bank_mask:0xf bound_ctrl:1
	ds_read_b128 v[68:71], v124 offset:46592
	v_add_f32_dpp v142, v142, v142 row_half_mirror row_mask:0xf bank_mask:0xf bound_ctrl:1
	v_add_f32_dpp v143, v143, v143 row_half_mirror row_mask:0xf bank_mask:0xf bound_ctrl:1
	ds_read_b128 v[56:59], v124 offset:46608
	ds_read_b32 v0, v135 offset:47360
	ds_read_b128 v[64:67], v124 offset:46848
	ds_read_b128 v[60:63], v124 offset:46864
	ds_read_b128 v[48:51], v124 offset:46080
	ds_read_b128 v[40:43], v124 offset:46096
	v_pk_mul_f32 v[182:183], v[182:183], v[142:143] op_sel_hi:[1,0]
	v_pk_mul_f32 v[184:185], v[184:185], v[142:143] op_sel_hi:[1,0]
	s_mov_b32 vcc_lo, 0x10101010
	v_pk_mul_f32 v[186:187], v[186:187], v[142:143] op_sel_hi:[1,0]
	v_pk_mul_f32 v[188:189], v[188:189], v[142:143] op_sel_hi:[1,0]
	s_mov_b32 vcc_hi, 0x10101010
	v_pk_fma_f32 v[190:191], v[190:191], v[160:161], v[182:183] op_sel_hi:[1,0,1] neg_lo:[0,0,1] neg_hi:[0,0,1]
	v_pk_fma_f32 v[192:193], v[192:193], v[160:161], v[184:185] op_sel_hi:[1,0,1] neg_lo:[0,0,1] neg_hi:[0,0,1]
	v_cndmask_b32_e32 v131, v131, v143, vcc
	v_pk_fma_f32 v[194:195], v[194:195], v[160:161], v[186:187] op_sel_hi:[1,0,1] neg_lo:[0,0,1] neg_hi:[0,0,1]
	v_pk_fma_f32 v[196:197], v[196:197], v[160:161], v[188:189] op_sel_hi:[1,0,1] neg_lo:[0,0,1] neg_hi:[0,0,1]
	ds_read_b128 v[52:55], v124 offset:47120
	ds_read_b128 v[44:47], v124 offset:47104
	v_pk_fma_f32 v[36:37], v[36:37], v[144:145], v[190:191]
	v_pk_fma_f32 v[38:39], v[38:39], v[146:147], v[192:193]
	v_pk_fma_f32 v[32:33], v[32:33], v[148:149], v[194:195]
	v_pk_fma_f32 v[34:35], v[34:35], v[150:151], v[196:197]
	s_waitcnt lgkmcnt(2)
	v_pk_mul_f32 v[76:77], v[32:33], v[76:77]
	v_pk_mul_f32 v[202:203], v[32:33], v[202:203]
	v_pk_mul_f32 v[78:79], v[34:35], v[78:79]
	v_pk_mul_f32 v[204:205], v[34:35], v[204:205]
	v_pk_fma_f32 v[72:73], v[36:37], v[72:73], v[76:77]
	v_pk_fma_f32 v[198:199], v[36:37], v[198:199], v[202:203]
	v_pk_fma_f32 v[74:75], v[38:39], v[74:75], v[78:79]
	v_pk_fma_f32 v[200:201], v[38:39], v[200:201], v[204:205]
	v_pk_add_f32 v[72:73], v[72:73], v[74:75]
	v_pk_add_f32 v[198:199], v[198:199], v[200:201]
	v_add_f32_e32 v142, v72, v73
	v_add_f32_e32 v143, v198, v199
	ds_read_b128 v[156:159], v124 offset:47888
	v_add_f32_dpp v142, v142, v142 quad_perm:[1,0,3,2] row_mask:0xf bank_mask:0xf bound_ctrl:1
	v_add_f32_dpp v143, v143, v143 quad_perm:[1,0,3,2] row_mask:0xf bank_mask:0xf bound_ctrl:1
	ds_read_b128 v[152:155], v124 offset:47872
	v_add_f32_dpp v142, v142, v142 quad_perm:[2,3,0,1] row_mask:0xf bank_mask:0xf bound_ctrl:1
	v_add_f32_dpp v143, v143, v143 quad_perm:[2,3,0,1] row_mask:0xf bank_mask:0xf bound_ctrl:1
	ds_read_b128 v[182:185], v124 offset:48128
	v_add_f32_dpp v142, v142, v142 row_half_mirror row_mask:0xf bank_mask:0xf bound_ctrl:1
	v_add_f32_dpp v143, v143, v143 row_half_mirror row_mask:0xf bank_mask:0xf bound_ctrl:1
	ds_read_b128 v[186:189], v124 offset:48144
	ds_read_b32 v160, v135 offset:48896
	ds_read_b128 v[190:193], v124 offset:48384
	ds_read_b128 v[194:197], v124 offset:48400
	ds_read_b128 v[144:147], v124 offset:47616
	ds_read_b128 v[148:151], v124 offset:47632
	v_pk_mul_f32 v[68:69], v[68:69], v[142:143] op_sel_hi:[1,0]
	v_pk_mul_f32 v[70:71], v[70:71], v[142:143] op_sel_hi:[1,0]
	s_mov_b32 vcc_lo, 0x20202020
	v_pk_mul_f32 v[56:57], v[56:57], v[142:143] op_sel_hi:[1,0]
	v_pk_mul_f32 v[58:59], v[58:59], v[142:143] op_sel_hi:[1,0]
	s_mov_b32 vcc_hi, 0x20202020
	v_pk_fma_f32 v[64:65], v[64:65], v[0:1], v[68:69] op_sel_hi:[1,0,1] neg_lo:[0,0,1] neg_hi:[0,0,1]
	v_pk_fma_f32 v[66:67], v[66:67], v[0:1], v[70:71] op_sel_hi:[1,0,1] neg_lo:[0,0,1] neg_hi:[0,0,1]
	v_cndmask_b32_e32 v131, v131, v143, vcc
	v_pk_fma_f32 v[60:61], v[60:61], v[0:1], v[56:57] op_sel_hi:[1,0,1] neg_lo:[0,0,1] neg_hi:[0,0,1]
	v_pk_fma_f32 v[62:63], v[62:63], v[0:1], v[58:59] op_sel_hi:[1,0,1] neg_lo:[0,0,1] neg_hi:[0,0,1]
	ds_read_b128 v[202:205], v124 offset:48656
	ds_read_b128 v[198:201], v124 offset:48640
	v_pk_fma_f32 v[36:37], v[36:37], v[48:49], v[64:65]
	v_pk_fma_f32 v[38:39], v[38:39], v[50:51], v[66:67]
	v_pk_fma_f32 v[32:33], v[32:33], v[40:41], v[60:61]
	v_pk_fma_f32 v[34:35], v[34:35], v[42:43], v[62:63]
	s_waitcnt lgkmcnt(2)
	v_pk_mul_f32 v[156:157], v[32:33], v[156:157]
	v_pk_mul_f32 v[52:53], v[32:33], v[52:53]
	v_pk_mul_f32 v[158:159], v[34:35], v[158:159]
	v_pk_mul_f32 v[54:55], v[34:35], v[54:55]
	v_pk_fma_f32 v[152:153], v[36:37], v[152:153], v[156:157]
	v_pk_fma_f32 v[44:45], v[36:37], v[44:45], v[52:53]
	v_pk_fma_f32 v[154:155], v[38:39], v[154:155], v[158:159]
	v_pk_fma_f32 v[46:47], v[38:39], v[46:47], v[54:55]
	v_pk_add_f32 v[152:153], v[152:153], v[154:155]
	v_pk_add_f32 v[44:45], v[44:45], v[46:47]
	v_add_f32_e32 v142, v152, v153
	v_add_f32_e32 v143, v44, v45
	s_nop 0
	v_add_f32_dpp v142, v142, v142 quad_perm:[1,0,3,2] row_mask:0xf bank_mask:0xf bound_ctrl:1
	v_add_f32_dpp v143, v143, v143 quad_perm:[1,0,3,2] row_mask:0xf bank_mask:0xf bound_ctrl:1
	s_nop 0
	v_add_f32_dpp v142, v142, v142 quad_perm:[2,3,0,1] row_mask:0xf bank_mask:0xf bound_ctrl:1
	v_add_f32_dpp v143, v143, v143 quad_perm:[2,3,0,1] row_mask:0xf bank_mask:0xf bound_ctrl:1
	s_nop 0
	v_add_f32_dpp v142, v142, v142 row_half_mirror row_mask:0xf bank_mask:0xf bound_ctrl:1
	v_add_f32_dpp v143, v143, v143 row_half_mirror row_mask:0xf bank_mask:0xf bound_ctrl:1
	v_pk_mul_f32 v[182:183], v[182:183], v[142:143] op_sel_hi:[1,0]
	v_pk_mul_f32 v[184:185], v[184:185], v[142:143] op_sel_hi:[1,0]
	s_mov_b32 vcc_lo, 0x40404040
	v_pk_mul_f32 v[186:187], v[186:187], v[142:143] op_sel_hi:[1,0]
	v_pk_mul_f32 v[188:189], v[188:189], v[142:143] op_sel_hi:[1,0]
	s_mov_b32 vcc_hi, 0x40404040
	v_pk_fma_f32 v[190:191], v[190:191], v[160:161], v[182:183] op_sel_hi:[1,0,1] neg_lo:[0,0,1] neg_hi:[0,0,1]
	v_pk_fma_f32 v[192:193], v[192:193], v[160:161], v[184:185] op_sel_hi:[1,0,1] neg_lo:[0,0,1] neg_hi:[0,0,1]
	v_cndmask_b32_e32 v131, v131, v143, vcc
	v_pk_fma_f32 v[194:195], v[194:195], v[160:161], v[186:187] op_sel_hi:[1,0,1] neg_lo:[0,0,1] neg_hi:[0,0,1]
	v_pk_fma_f32 v[196:197], v[196:197], v[160:161], v[188:189] op_sel_hi:[1,0,1] neg_lo:[0,0,1] neg_hi:[0,0,1]
	v_pk_fma_f32 v[36:37], v[36:37], v[144:145], v[190:191]
	v_pk_fma_f32 v[38:39], v[38:39], v[146:147], v[192:193]
	v_pk_fma_f32 v[32:33], v[32:33], v[148:149], v[194:195]
	v_pk_fma_f32 v[34:35], v[34:35], v[150:151], v[196:197]
	s_waitcnt lgkmcnt(0)
	v_pk_mul_f32 v[202:203], v[32:33], v[202:203]
	v_pk_mul_f32 v[204:205], v[34:35], v[204:205]
	v_pk_fma_f32 v[198:199], v[36:37], v[198:199], v[202:203]
	v_pk_fma_f32 v[200:201], v[38:39], v[200:201], v[204:205]
	v_pk_add_f32 v[198:199], v[198:199], v[200:201]
	v_add_f32_e32 v143, v198, v199
	s_nop 1
	v_add_f32_dpp v143, v143, v143 quad_perm:[1,0,3,2] row_mask:0xf bank_mask:0xf bound_ctrl:1
	s_nop 1
	v_add_f32_dpp v143, v143, v143 quad_perm:[2,3,0,1] row_mask:0xf bank_mask:0xf bound_ctrl:1
	s_nop 1
	v_add_f32_dpp v143, v143, v143 row_half_mirror row_mask:0xf bank_mask:0xf bound_ctrl:1
	s_mov_b32 vcc_lo, 0x80808080
	s_mov_b32 vcc_hi, 0x80808080
	v_cndmask_b32_e32 v131, v131, v143, vcc
	s_setprio 0
	s_lshl_b32 s70, s64, 5
	s_add_u32 s70, s70, s4
	v_add_u32_e32 v40, s70, v86
	v_lshlrev_b32_e32 v46, 1, v112
	v_mul_u32_u24_e32 v41, 0xc00, v40
	v_add_u32_e32 v41, v41, v46
	v_bfe_u32 v47, v134, 16, 1
	v_add3_u32 v47, v134, v47, s78
	global_store_short_d16_hi v41, v47, s[60:61]
	v_bfe_u32 v47, v133, 16, 1
	v_add3_u32 v47, v133, v47, s78
	v_add_u32_e32 v45, 0x6000, v41
	global_store_short_d16_hi v45, v47, s[60:61]
	v_bfe_u32 v47, v132, 16, 1
	v_add3_u32 v47, v132, v47, s78
	v_add_u32_e32 v45, 0xc000, v41
	global_store_short_d16_hi v45, v47, s[60:61]
	v_bfe_u32 v47, v131, 16, 1
	v_add3_u32 v47, v131, v47, s78
	v_add_u32_e32 v45, 0x12000, v41
	global_store_short_d16_hi v45, v47, s[60:61]
	s_branch .LBB0_631
